# x3 + GEMM main loops: F1 LDS-DMAs (uniform base + zero-extended 32-bit lane offset) in saddr form, v_lshl_add_u64 dropped
# baseline (speedup 1.0000x reference)
; #define PG8_STAGE(bufoff, gbase, voff) do { _Pragma("unroll") for (int _i = 0; _i < 2; ++_i) \
;         __builtin_amdgcn_global_load_lds((const unsigned*)((const char*)(gbase) + (voff)[_i]), (PG8_LAS unsigned*)(lds + (bufoff) + ldsw + _i * 8192), 16, 0, 0); } while (0)
; #define PG8_WAIT_V(n) asm volatile("s_waitcnt vmcnt(" #n ")" ::: "memory")
; #define PG8_WAIT_L(n) asm volatile("s_waitcnt lgkmcnt(" #n ")" ::: "memory")
; #define PG8_BAR __builtin_amdgcn_s_barrier()
; #define PG8_SCHED __builtin_amdgcn_sched_barrier(0)
; #define PG8_STAGEA(bufoff, gbase, h, vsel) do { if constexpr (GATHER) { PG8_STAGE(bufoff, gbase, vsel[h]); } else { PG8_STAGE(bufoff, (gbase) + (h) * hstep, voffA); } } while (0)
; template <class Epi, class Sched, bool ALIGN_EPI = false, bool SP2 = false, bool F8 = false, bool GATHER = false>
; __device__ __forceinline__ void gemm_phase(PG8_LAS unsigned char* lds, const Gemm g, const Sched& S, const Epi& E, const int tid_in) {
;     ...
;             PG8_LDB(B0, 0, 0); PG8_LDB(B1, 0, 1); PG8_SCHED; PG8_LDA(At, 0, 0); PG8_STAGEA(PG8_SA(1, 1), a1, 1, vC);
;             PG8_WAIT_V(8); PG8_WAIT_L(0); PG8_BAR; PG8_MMA(0, 0, At, B0); PG8_MMA(0, 1, At, B1); PG8_BAR; PG8_SCHED;
;             PG8_LDA(At, 0, 1); PG8_STAGE(PG8_SB(0, 0), b2, voffB); PG8_STAGE(PG8_SB(0, 1), b2 + hstep, voffB); PG8_STAGEA(PG8_SA(0, 0), a2, 0, vS);
.LBB0_183:
	s_add_u32 s6, s2, 0xfffc0080
	s_addc_u32 s7, s3, -1
	s_add_i32 s35, 0, 0x10000
	s_cmp_eq_u32 s33, 12
	s_cselect_b32 s13, s9, s7
	s_cselect_b32 s12, s11, s6
	v_add_u32_e32 v0, s35, v152
	s_cselect_b32 s7, s16, s15
	s_cselect_b32 s6, s17, s14
	s_add_i32 s51, 0, 0x14000
	ds_read_b128 v[138:141], v0
	ds_read_b128 v[142:145], v0 offset:1024
	ds_read_b128 v[146:149], v0 offset:2048
	ds_read_b128 v[154:157], v0 offset:3072
	v_add_u32_e32 v0, s51, v152
	ds_read_b128 v[158:161], v0
	ds_read_b128 v[162:165], v0 offset:1024
	ds_read_b128 v[166:169], v0 offset:2048
	ds_read_b128 v[170:173], v0 offset:3072
	s_add_i32 m0, s85, 0xc000
	ds_read_b128 v[174:177], v153
	ds_read_b128 v[178:181], v153 offset:1024
	ds_read_b128 v[182:185], v153 offset:2048
	ds_read_b128 v[186:189], v153 offset:3072
	ds_read_b128 v[190:193], v153 offset:4096
	ds_read_b128 v[194:197], v153 offset:5120
	ds_read_b128 v[198:201], v153 offset:6144
	ds_read_b128 v[202:205], v153 offset:7168
	global_load_lds_dwordx4 v134, s[2:3]
	s_add_i32 m0, s85, 0xe000
	s_nop 0
	global_load_lds_dwordx4 v136, s[2:3]
	s_waitcnt vmcnt(8)
	s_waitcnt lgkmcnt(0)
	s_barrier
	s_setprio 1
	s_waitcnt lgkmcnt(0)
	v_mfma_f32_16x16x32_bf16 v[126:129], v[138:141], v[174:177], v[126:129]
	v_mfma_f32_16x16x32_bf16 v[118:121], v[146:149], v[174:177], v[118:121]
	v_mfma_f32_16x16x32_bf16 v[110:113], v[138:141], v[182:185], v[110:113]
	v_mfma_f32_16x16x32_bf16 v[102:105], v[146:149], v[182:185], v[102:105]
	v_mfma_f32_16x16x32_bf16 v[94:97], v[138:141], v[190:193], v[94:97]
	v_mfma_f32_16x16x32_bf16 v[86:89], v[146:149], v[190:193], v[86:89]
	v_mfma_f32_16x16x32_bf16 v[78:81], v[138:141], v[198:201], v[78:81]
	v_mfma_f32_16x16x32_bf16 v[70:73], v[146:149], v[198:201], v[70:73]
	v_mfma_f32_16x16x32_bf16 v[126:129], v[142:145], v[178:181], v[126:129]
	v_mfma_f32_16x16x32_bf16 v[118:121], v[154:157], v[178:181], v[118:121]
	v_mfma_f32_16x16x32_bf16 v[110:113], v[142:145], v[186:189], v[110:113]
	v_mfma_f32_16x16x32_bf16 v[102:105], v[154:157], v[186:189], v[102:105]
	v_mfma_f32_16x16x32_bf16 v[94:97], v[142:145], v[194:197], v[94:97]
	v_mfma_f32_16x16x32_bf16 v[86:89], v[154:157], v[194:197], v[86:89]
	v_mfma_f32_16x16x32_bf16 v[78:81], v[142:145], v[202:205], v[78:81]
	v_mfma_f32_16x16x32_bf16 v[70:73], v[154:157], v[202:205], v[70:73]
	s_setprio 0
	s_setprio 1
	v_mfma_f32_16x16x32_bf16 v[114:117], v[158:161], v[174:177], v[114:117]
	v_mfma_f32_16x16x32_bf16 v[122:125], v[166:169], v[174:177], v[122:125]
	v_mfma_f32_16x16x32_bf16 v[98:101], v[158:161], v[182:185], v[98:101]
	v_mfma_f32_16x16x32_bf16 v[106:109], v[166:169], v[182:185], v[106:109]
	v_mfma_f32_16x16x32_bf16 v[82:85], v[158:161], v[190:193], v[82:85]
	v_mfma_f32_16x16x32_bf16 v[90:93], v[166:169], v[190:193], v[90:93]
	v_mfma_f32_16x16x32_bf16 v[66:69], v[158:161], v[198:201], v[66:69]
	v_mfma_f32_16x16x32_bf16 v[74:77], v[166:169], v[198:201], v[74:77]
	v_mfma_f32_16x16x32_bf16 v[114:117], v[162:165], v[178:181], v[114:117]
	v_mfma_f32_16x16x32_bf16 v[122:125], v[170:173], v[178:181], v[122:125]
	v_mfma_f32_16x16x32_bf16 v[98:101], v[162:165], v[186:189], v[98:101]
	v_mfma_f32_16x16x32_bf16 v[106:109], v[170:173], v[186:189], v[106:109]
	v_mfma_f32_16x16x32_bf16 v[82:85], v[162:165], v[194:197], v[82:85]
	v_mfma_f32_16x16x32_bf16 v[90:93], v[170:173], v[194:197], v[90:93]
	v_mfma_f32_16x16x32_bf16 v[66:69], v[162:165], v[202:205], v[66:69]
	v_mfma_f32_16x16x32_bf16 v[74:77], v[170:173], v[202:205], v[74:77]
	s_setprio 0
	s_barrier
	s_add_i32 s35, s35, s84
	v_lshl_add_u64 v[206:207], s[6:7], 0, v[130:131]
	s_mov_b32 m0, s35
	ds_read_b128 v[174:177], v153 offset:16384
	ds_read_b128 v[178:181], v153 offset:17408
	ds_read_b128 v[182:185], v153 offset:18432
	ds_read_b128 v[186:189], v153 offset:19456
	ds_read_b128 v[190:193], v153 offset:20480
	ds_read_b128 v[194:197], v153 offset:21504
	ds_read_b128 v[198:201], v153 offset:22528
	ds_read_b128 v[202:205], v153 offset:23552
	global_load_lds_dwordx4 v130, s[6:7]
	s_add_i32 m0, s35, 0x2000
	s_add_u32 s52, s6, 0x40000
	v_lshl_add_u64 v[208:209], s[6:7], 0, v[132:133]
	s_addc_u32 s53, s7, 0
	s_add_i32 s35, s51, s84
	global_load_lds_dwordx4 v132, s[6:7]
	s_mov_b32 m0, s35
	v_lshl_add_u64 v[212:213], s[12:13], 0, v[132:133]
	global_load_lds_dwordx4 v130, s[52:53]
	s_add_i32 m0, s35, 0x2000
	s_nop 0
	global_load_lds_dwordx4 v132, s[52:53]
	v_lshl_add_u64 v[210:211], s[12:13], 0, v[130:131]
	s_mov_b32 m0, s85
	s_nop 0
	global_load_lds_dwordx4 v130, s[12:13]
	s_mov_b32 m0, s86
	s_nop 0
	global_load_lds_dwordx4 v132, s[12:13]
	s_waitcnt vmcnt(8)
	s_waitcnt lgkmcnt(0)
	s_barrier
; #define PG8_WAIT_V(n) asm volatile("s_waitcnt vmcnt(" #n ")" ::: "memory")
; #define PG8_WAIT_L(n) asm volatile("s_waitcnt lgkmcnt(" #n ")" ::: "memory")
; #define PG8_BAR __builtin_amdgcn_s_barrier()
; #define PG8_SCHED __builtin_amdgcn_sched_barrier(0)
; #define PG8_STAGEA(bufoff, gbase, h, vsel) do { if constexpr (GATHER) { PG8_STAGE(bufoff, gbase, vsel[h]); } else { PG8_STAGE(bufoff, (gbase) + (h) * hstep, voffA); } } while (0)
; template <class Epi, class Sched, bool ALIGN_EPI = false, bool SP2 = false, bool F8 = false, bool GATHER = false>
; __device__ __forceinline__ void gemm_phase(PG8_LAS unsigned char* lds, const Gemm g, const Sched& S, const Epi& E, const int tid_in) {
;     ...
;             PG8_WAIT_V(8); PG8_WAIT_L(0); PG8_BAR; PG8_MMA(1, 0, At, B0); PG8_MMA(1, 1, At, B1); PG8_BAR; PG8_SCHED;
;             PG8_LDB(B0, 1, 0); PG8_LDB(B1, 1, 1); PG8_SCHED; PG8_LDA(At, 1, 0); PG8_STAGEA(PG8_SA(0, 1), a2, 1, vS);
;             PG8_WAIT_V(8); PG8_WAIT_L(0); PG8_BAR; PG8_MMA(0, 0, At, B0); PG8_MMA(0, 1, At, B1); PG8_BAR; PG8_SCHED;
	s_setprio 1
	s_waitcnt lgkmcnt(0)
	v_mfma_f32_16x16x32_bf16 v[62:65], v[138:141], v[174:177], v[62:65]
	v_mfma_f32_16x16x32_bf16 v[54:57], v[146:149], v[174:177], v[54:57]
	v_mfma_f32_16x16x32_bf16 v[46:49], v[138:141], v[182:185], v[46:49]
	v_mfma_f32_16x16x32_bf16 v[38:41], v[146:149], v[182:185], v[38:41]
	v_mfma_f32_16x16x32_bf16 v[30:33], v[138:141], v[190:193], v[30:33]
	v_mfma_f32_16x16x32_bf16 v[22:25], v[146:149], v[190:193], v[22:25]
	v_mfma_f32_16x16x32_bf16 v[14:17], v[138:141], v[198:201], v[14:17]
	v_mfma_f32_16x16x32_bf16 v[6:9], v[146:149], v[198:201], v[6:9]
	v_mfma_f32_16x16x32_bf16 v[62:65], v[142:145], v[178:181], v[62:65]
	v_mfma_f32_16x16x32_bf16 v[54:57], v[154:157], v[178:181], v[54:57]
	v_mfma_f32_16x16x32_bf16 v[46:49], v[142:145], v[186:189], v[46:49]
	v_mfma_f32_16x16x32_bf16 v[38:41], v[154:157], v[186:189], v[38:41]
	v_mfma_f32_16x16x32_bf16 v[30:33], v[142:145], v[194:197], v[30:33]
	v_mfma_f32_16x16x32_bf16 v[22:25], v[154:157], v[194:197], v[22:25]
	v_mfma_f32_16x16x32_bf16 v[14:17], v[142:145], v[202:205], v[14:17]
	v_mfma_f32_16x16x32_bf16 v[6:9], v[154:157], v[202:205], v[6:9]
	s_setprio 0
	s_setprio 1
	v_mfma_f32_16x16x32_bf16 v[50:53], v[158:161], v[174:177], v[50:53]
	v_mfma_f32_16x16x32_bf16 v[58:61], v[166:169], v[174:177], v[58:61]
	v_mfma_f32_16x16x32_bf16 v[34:37], v[158:161], v[182:185], v[34:37]
	v_mfma_f32_16x16x32_bf16 v[42:45], v[166:169], v[182:185], v[42:45]
	v_mfma_f32_16x16x32_bf16 v[18:21], v[158:161], v[190:193], v[18:21]
	v_mfma_f32_16x16x32_bf16 v[26:29], v[166:169], v[190:193], v[26:29]
	v_mfma_f32_16x16x32_bf16 v[2:5], v[158:161], v[198:201], v[2:5]
	v_mfma_f32_16x16x32_bf16 v[10:13], v[166:169], v[198:201], v[10:13]
	v_mfma_f32_16x16x32_bf16 v[50:53], v[162:165], v[178:181], v[50:53]
	v_mfma_f32_16x16x32_bf16 v[58:61], v[170:173], v[178:181], v[58:61]
	v_mfma_f32_16x16x32_bf16 v[34:37], v[162:165], v[186:189], v[34:37]
	v_mfma_f32_16x16x32_bf16 v[42:45], v[170:173], v[186:189], v[42:45]
	v_mfma_f32_16x16x32_bf16 v[18:21], v[162:165], v[194:197], v[18:21]
	v_mfma_f32_16x16x32_bf16 v[26:29], v[170:173], v[194:197], v[26:29]
	v_mfma_f32_16x16x32_bf16 v[2:5], v[162:165], v[202:205], v[2:5]
	v_mfma_f32_16x16x32_bf16 v[10:13], v[170:173], v[202:205], v[10:13]
	s_setprio 0
	s_barrier
	s_add_i32 s35, 0, 0x18000
	v_add_u32_e32 v0, s35, v152
	s_add_i32 s51, 0, 0x1c000
	ds_read_b128 v[138:141], v0
	ds_read_b128 v[142:145], v0 offset:1024
	ds_read_b128 v[146:149], v0 offset:2048
	ds_read_b128 v[154:157], v0 offset:3072
	v_add_u32_e32 v0, s51, v152
	ds_read_b128 v[158:161], v0
	ds_read_b128 v[162:165], v0 offset:1024
	ds_read_b128 v[166:169], v0 offset:2048
	ds_read_b128 v[170:173], v0 offset:3072
	s_add_u32 s12, s12, 0x40000
	s_addc_u32 s13, s13, 0
	s_mov_b32 m0, s87
	ds_read_b128 v[174:177], v153 offset:32768
	ds_read_b128 v[178:181], v153 offset:33792
	ds_read_b128 v[182:185], v153 offset:34816
	ds_read_b128 v[186:189], v153 offset:35840
	ds_read_b128 v[190:193], v153 offset:36864
	ds_read_b128 v[194:197], v153 offset:37888
	ds_read_b128 v[198:201], v153 offset:38912
	ds_read_b128 v[202:205], v153 offset:39936
	global_load_lds_dwordx4 v130, s[12:13]
	s_mov_b32 m0, s88
	s_nop 0
	global_load_lds_dwordx4 v132, s[12:13]
	s_waitcnt vmcnt(8)
	s_waitcnt lgkmcnt(0)
	s_barrier
	s_setprio 1
	s_waitcnt lgkmcnt(0)
	v_mfma_f32_16x16x32_bf16 v[126:129], v[138:141], v[174:177], v[126:129]
	v_mfma_f32_16x16x32_bf16 v[118:121], v[146:149], v[174:177], v[118:121]
	v_mfma_f32_16x16x32_bf16 v[110:113], v[138:141], v[182:185], v[110:113]
	v_mfma_f32_16x16x32_bf16 v[102:105], v[146:149], v[182:185], v[102:105]
	v_mfma_f32_16x16x32_bf16 v[94:97], v[138:141], v[190:193], v[94:97]
	v_mfma_f32_16x16x32_bf16 v[86:89], v[146:149], v[190:193], v[86:89]
	v_mfma_f32_16x16x32_bf16 v[78:81], v[138:141], v[198:201], v[78:81]
	v_mfma_f32_16x16x32_bf16 v[70:73], v[146:149], v[198:201], v[70:73]
	v_mfma_f32_16x16x32_bf16 v[126:129], v[142:145], v[178:181], v[126:129]
	v_mfma_f32_16x16x32_bf16 v[118:121], v[154:157], v[178:181], v[118:121]
	v_mfma_f32_16x16x32_bf16 v[110:113], v[142:145], v[186:189], v[110:113]
	v_mfma_f32_16x16x32_bf16 v[102:105], v[154:157], v[186:189], v[102:105]
	v_mfma_f32_16x16x32_bf16 v[94:97], v[142:145], v[194:197], v[94:97]
	v_mfma_f32_16x16x32_bf16 v[86:89], v[154:157], v[194:197], v[86:89]
	v_mfma_f32_16x16x32_bf16 v[78:81], v[142:145], v[202:205], v[78:81]
	v_mfma_f32_16x16x32_bf16 v[70:73], v[154:157], v[202:205], v[70:73]
	s_setprio 0
	s_setprio 1
	v_mfma_f32_16x16x32_bf16 v[114:117], v[158:161], v[174:177], v[114:117]
	v_mfma_f32_16x16x32_bf16 v[122:125], v[166:169], v[174:177], v[122:125]
	v_mfma_f32_16x16x32_bf16 v[98:101], v[158:161], v[182:185], v[98:101]
	v_mfma_f32_16x16x32_bf16 v[106:109], v[166:169], v[182:185], v[106:109]
	v_mfma_f32_16x16x32_bf16 v[82:85], v[158:161], v[190:193], v[82:85]
	v_mfma_f32_16x16x32_bf16 v[90:93], v[166:169], v[190:193], v[90:93]
	v_mfma_f32_16x16x32_bf16 v[66:69], v[158:161], v[198:201], v[66:69]
	v_mfma_f32_16x16x32_bf16 v[74:77], v[166:169], v[198:201], v[74:77]
	v_mfma_f32_16x16x32_bf16 v[114:117], v[162:165], v[178:181], v[114:117]
	v_mfma_f32_16x16x32_bf16 v[122:125], v[170:173], v[178:181], v[122:125]
	v_mfma_f32_16x16x32_bf16 v[98:101], v[162:165], v[186:189], v[98:101]
	v_mfma_f32_16x16x32_bf16 v[106:109], v[170:173], v[186:189], v[106:109]
	v_mfma_f32_16x16x32_bf16 v[82:85], v[162:165], v[194:197], v[82:85]
	v_mfma_f32_16x16x32_bf16 v[90:93], v[170:173], v[194:197], v[90:93]
	v_mfma_f32_16x16x32_bf16 v[66:69], v[162:165], v[202:205], v[66:69]
	v_mfma_f32_16x16x32_bf16 v[74:77], v[170:173], v[202:205], v[74:77]
	s_setprio 0
	s_barrier
; #define PG8_STAGE(bufoff, gbase, voff) do { _Pragma("unroll") for (int _i = 0; _i < 2; ++_i) \
;         __builtin_amdgcn_global_load_lds((const unsigned*)((const char*)(gbase) + (voff)[_i]), (PG8_LAS unsigned*)(lds + (bufoff) + ldsw + _i * 8192), 16, 0, 0); } while (0)
; #define PG8_WAIT_V(n) asm volatile("s_waitcnt vmcnt(" #n ")" ::: "memory")
; #define PG8_WAIT_L(n) asm volatile("s_waitcnt lgkmcnt(" #n ")" ::: "memory")
; #define PG8_BAR __builtin_amdgcn_s_barrier()
; #define PG8_SCHED __builtin_amdgcn_sched_barrier(0)
; #define PG8_STAGEA(bufoff, gbase, h, vsel) do { if constexpr (GATHER) { PG8_STAGE(bufoff, gbase, vsel[h]); } else { PG8_STAGE(bufoff, (gbase) + (h) * hstep, voffA); } } while (0)
; template <class Epi, class Sched, bool ALIGN_EPI = false, bool SP2 = false, bool F8 = false, bool GATHER = false>
; __device__ __forceinline__ void gemm_phase(PG8_LAS unsigned char* lds, const Gemm g, const Sched& S, const Epi& E, const int tid_in) {
;     ...
;         for (int t = 0; t < nt; t += 2) {
;             const bool last = (t == nt - 2);
;             const char* a1 = cA + (size_t)(t + 1) * kstep;
;             const char* a2 = last ? nA : cA + (size_t)(t + 2) * kstep; const char* b2 = last ? nB : cB + (size_t)(t + 2) * kstep;
;             const char* a3 = a2 + kstep; const char* b3 = b2 + kstep;
;     ...
;             PG8_LDA(At, 1, 1); PG8_STAGE(PG8_SB(1, 0), b3, voffB); PG8_STAGE(PG8_SB(1, 1), b3 + hstep, voffB); PG8_STAGEA(PG8_SA(1, 0), a3, 0, vS);
;             PG8_WAIT_V(8); PG8_WAIT_L(0); PG8_BAR; PG8_MMA(1, 0, At, B0); PG8_MMA(1, 1, At, B1); PG8_BAR; PG8_SCHED;
	s_add_i32 s12, s35, s84
	v_lshl_add_u64 v[206:207], v[206:207], 0, s[0:1]
	s_mov_b32 m0, s12
	ds_read_b128 v[174:177], v153 offset:49152
	ds_read_b128 v[178:181], v153 offset:50176
	ds_read_b128 v[182:185], v153 offset:51200
	ds_read_b128 v[186:189], v153 offset:52224
	ds_read_b128 v[190:193], v153 offset:53248
	ds_read_b128 v[194:197], v153 offset:54272
	ds_read_b128 v[198:201], v153 offset:55296
	ds_read_b128 v[202:205], v153 offset:56320
	global_load_lds_dwordx4 v[206:207], off
	s_add_i32 m0, s12, 0x2000
	s_add_u32 s6, s6, 0x40080
	v_lshl_add_u64 v[206:207], v[208:209], 0, s[0:1]
	s_addc_u32 s7, s7, 0
	s_add_i32 s12, s51, s84
	global_load_lds_dwordx4 v[206:207], off
	s_mov_b32 m0, s12
	s_nop 0
	global_load_lds_dwordx4 v130, s[6:7]
	s_add_i32 m0, s12, 0x2000
	s_nop 0
	global_load_lds_dwordx4 v132, s[6:7]
	v_lshl_add_u64 v[206:207], v[210:211], 0, s[0:1]
	s_mov_b32 m0, s91
	s_nop 0
	global_load_lds_dwordx4 v[206:207], off
	v_lshl_add_u64 v[206:207], v[212:213], 0, s[0:1]
	s_mov_b32 m0, s94
	s_nop 0
	global_load_lds_dwordx4 v[206:207], off
	s_waitcnt vmcnt(8)
	s_waitcnt lgkmcnt(0)
	s_barrier
	s_setprio 1
	s_waitcnt lgkmcnt(0)
	v_mfma_f32_16x16x32_bf16 v[62:65], v[138:141], v[174:177], v[62:65]
	v_mfma_f32_16x16x32_bf16 v[54:57], v[146:149], v[174:177], v[54:57]
	v_mfma_f32_16x16x32_bf16 v[46:49], v[138:141], v[182:185], v[46:49]
	v_mfma_f32_16x16x32_bf16 v[38:41], v[146:149], v[182:185], v[38:41]
	v_mfma_f32_16x16x32_bf16 v[30:33], v[138:141], v[190:193], v[30:33]
	v_mfma_f32_16x16x32_bf16 v[22:25], v[146:149], v[190:193], v[22:25]
	v_mfma_f32_16x16x32_bf16 v[14:17], v[138:141], v[198:201], v[14:17]
	v_mfma_f32_16x16x32_bf16 v[6:9], v[146:149], v[198:201], v[6:9]
	v_mfma_f32_16x16x32_bf16 v[62:65], v[142:145], v[178:181], v[62:65]
	v_mfma_f32_16x16x32_bf16 v[54:57], v[154:157], v[178:181], v[54:57]
	v_mfma_f32_16x16x32_bf16 v[46:49], v[142:145], v[186:189], v[46:49]
	v_mfma_f32_16x16x32_bf16 v[38:41], v[154:157], v[186:189], v[38:41]
	v_mfma_f32_16x16x32_bf16 v[30:33], v[142:145], v[194:197], v[30:33]
	v_mfma_f32_16x16x32_bf16 v[22:25], v[154:157], v[194:197], v[22:25]
	v_mfma_f32_16x16x32_bf16 v[14:17], v[142:145], v[202:205], v[14:17]
	v_mfma_f32_16x16x32_bf16 v[6:9], v[154:157], v[202:205], v[6:9]
	s_setprio 0
	s_setprio 1
	v_mfma_f32_16x16x32_bf16 v[50:53], v[158:161], v[174:177], v[50:53]
	v_mfma_f32_16x16x32_bf16 v[58:61], v[166:169], v[174:177], v[58:61]
	v_mfma_f32_16x16x32_bf16 v[34:37], v[158:161], v[182:185], v[34:37]
	v_mfma_f32_16x16x32_bf16 v[42:45], v[166:169], v[182:185], v[42:45]
	v_mfma_f32_16x16x32_bf16 v[18:21], v[158:161], v[190:193], v[18:21]
	v_mfma_f32_16x16x32_bf16 v[26:29], v[166:169], v[190:193], v[26:29]
	v_mfma_f32_16x16x32_bf16 v[2:5], v[158:161], v[198:201], v[2:5]
	v_mfma_f32_16x16x32_bf16 v[10:13], v[166:169], v[198:201], v[10:13]
	v_mfma_f32_16x16x32_bf16 v[50:53], v[162:165], v[178:181], v[50:53]
	v_mfma_f32_16x16x32_bf16 v[58:61], v[170:173], v[178:181], v[58:61]
	v_mfma_f32_16x16x32_bf16 v[34:37], v[162:165], v[186:189], v[34:37]
	v_mfma_f32_16x16x32_bf16 v[42:45], v[170:173], v[186:189], v[42:45]
	v_mfma_f32_16x16x32_bf16 v[18:21], v[162:165], v[194:197], v[18:21]
	v_mfma_f32_16x16x32_bf16 v[26:29], v[170:173], v[194:197], v[26:29]
	v_mfma_f32_16x16x32_bf16 v[2:5], v[162:165], v[202:205], v[2:5]
	v_mfma_f32_16x16x32_bf16 v[10:13], v[170:173], v[202:205], v[10:13]
	s_setprio 0
	s_barrier
	s_add_i32 s33, s33, 2
	s_add_u32 s2, s2, 0x100
	s_addc_u32 s3, s3, 0
	s_add_u32 s14, s14, 0x100
	s_addc_u32 s15, s15, 0
	s_cmp_gt_u32 s33, 13
	s_cbranch_scc0 .LBB0_183
	s_and_b64 vcc, exec, s[26:27]
	s_cbranch_vccz .LBB0_186
	s_barrier

; #define PG8_STAGE(bufoff, gbase, voff) do { _Pragma("unroll") for (int _i = 0; _i < 2; ++_i) \
;         __builtin_amdgcn_global_load_lds((const unsigned*)((const char*)(gbase) + (voff)[_i]), (PG8_LAS unsigned*)(lds + (bufoff) + ldsw + _i * 8192), 16, 0, 0); } while (0)
; #define PG8_WAIT_V(n) asm volatile("s_waitcnt vmcnt(" #n ")" ::: "memory")
; #define PG8_WAIT_L(n) asm volatile("s_waitcnt lgkmcnt(" #n ")" ::: "memory")
; #define PG8_BAR __builtin_amdgcn_s_barrier()
; #define PG8_SCHED __builtin_amdgcn_sched_barrier(0)
; #define PG8_STAGEA(bufoff, gbase, h, vsel) do { if constexpr (GATHER) { PG8_STAGE(bufoff, gbase, vsel[h]); } else { PG8_STAGE(bufoff, (gbase) + (h) * hstep, voffA); } } while (0)
; template <class Epi, class Sched, bool ALIGN_EPI = false, bool SP2 = false, bool F8 = false, bool GATHER = false>
; __device__ __forceinline__ void gemm_phase(PG8_LAS unsigned char* lds, const Gemm g, const Sched& S, const Epi& E, const int tid_in) {
;     ...
;             PG8_LDB(B0, 0, 0); PG8_LDB(B1, 0, 1); PG8_SCHED; PG8_LDA(At, 0, 0); PG8_STAGEA(PG8_SA(1, 1), a1, 1, vC);
;             PG8_WAIT_V(8); PG8_WAIT_L(0); PG8_BAR; PG8_MMA(0, 0, At, B0); PG8_MMA(0, 1, At, B1); PG8_BAR; PG8_SCHED;
;             PG8_LDA(At, 0, 1); PG8_STAGE(PG8_SB(0, 0), b2, voffB); PG8_STAGE(PG8_SB(0, 1), b2 + hstep, voffB); PG8_STAGEA(PG8_SA(0, 0), a2, 0, vS);
.LBB0_423:
	s_add_u32 s26, s24, 0xfffe0080
	s_addc_u32 s27, s25, -1
	s_add_i32 s49, 0, 0x10000
	s_cmp_eq_u32 s48, 4
	s_cselect_b32 s29, s13, s27
	s_cselect_b32 s28, s44, s26
	v_add_u32_e32 v136, s49, v145
	s_cselect_b32 s27, s11, s47
	s_cselect_b32 s26, s45, s46
	s_add_i32 s52, 0, 0x14000
	ds_read_b128 v[148:151], v136
	ds_read_b128 v[152:155], v136 offset:1024
	ds_read_b128 v[156:159], v136 offset:2048
	ds_read_b128 v[160:163], v136 offset:3072
	v_add_u32_e32 v136, s52, v145
	ds_read_b128 v[164:167], v136
	ds_read_b128 v[168:171], v136 offset:1024
	ds_read_b128 v[172:175], v136 offset:2048
	ds_read_b128 v[176:179], v136 offset:3072
	s_add_i32 m0, s23, 0xc000
	ds_read_b128 v[136:139], v147
	ds_read_b128 v[140:143], v147 offset:1024
	ds_read_b128 v[180:183], v147 offset:2048
	ds_read_b128 v[184:187], v147 offset:3072
	ds_read_b128 v[188:191], v147 offset:4096
	ds_read_b128 v[192:195], v147 offset:5120
	ds_read_b128 v[196:199], v147 offset:6144
	ds_read_b128 v[200:203], v147 offset:7168
	global_load_lds_dwordx4 v132, s[24:25]
	s_add_i32 m0, s23, 0xe000
	s_nop 0
	global_load_lds_dwordx4 v134, s[24:25]
	s_waitcnt vmcnt(8)
	s_waitcnt lgkmcnt(0)
	s_barrier
	s_setprio 1
	s_waitcnt lgkmcnt(0)
	v_mfma_scale_f32_16x16x128_f8f6f4 v[126:129], v[148:155], v[136:143], v[126:129], v235, v235 op_sel_hi:[0,0,0]
	v_mfma_scale_f32_16x16x128_f8f6f4 v[122:125], v[156:163], v[136:143], v[122:125], v235, v235 op_sel_hi:[0,0,0]
	v_mfma_scale_f32_16x16x128_f8f6f4 v[110:113], v[148:155], v[180:187], v[110:113], v235, v235 op_sel_hi:[0,0,0]
	v_mfma_scale_f32_16x16x128_f8f6f4 v[106:109], v[156:163], v[180:187], v[106:109], v235, v235 op_sel_hi:[0,0,0]
	v_mfma_scale_f32_16x16x128_f8f6f4 v[94:97], v[148:155], v[188:195], v[94:97], v235, v235 op_sel_hi:[0,0,0]
	v_mfma_scale_f32_16x16x128_f8f6f4 v[90:93], v[156:163], v[188:195], v[90:93], v235, v235 op_sel_hi:[0,0,0]
	v_mfma_scale_f32_16x16x128_f8f6f4 v[78:81], v[148:155], v[196:203], v[78:81], v235, v235 op_sel_hi:[0,0,0]
	v_mfma_scale_f32_16x16x128_f8f6f4 v[74:77], v[156:163], v[196:203], v[74:77], v235, v235 op_sel_hi:[0,0,0]
	s_setprio 0
	s_setprio 1
	v_mfma_scale_f32_16x16x128_f8f6f4 v[118:121], v[164:171], v[136:143], v[118:121], v235, v235 op_sel_hi:[0,0,0]
	v_mfma_scale_f32_16x16x128_f8f6f4 v[114:117], v[172:179], v[136:143], v[114:117], v235, v235 op_sel_hi:[0,0,0]
	v_mfma_scale_f32_16x16x128_f8f6f4 v[102:105], v[164:171], v[180:187], v[102:105], v235, v235 op_sel_hi:[0,0,0]
	v_mfma_scale_f32_16x16x128_f8f6f4 v[98:101], v[172:179], v[180:187], v[98:101], v235, v235 op_sel_hi:[0,0,0]
	v_mfma_scale_f32_16x16x128_f8f6f4 v[86:89], v[164:171], v[188:195], v[86:89], v235, v235 op_sel_hi:[0,0,0]
	v_mfma_scale_f32_16x16x128_f8f6f4 v[82:85], v[172:179], v[188:195], v[82:85], v235, v235 op_sel_hi:[0,0,0]
	v_mfma_scale_f32_16x16x128_f8f6f4 v[70:73], v[164:171], v[196:203], v[70:73], v235, v235 op_sel_hi:[0,0,0]
	v_mfma_scale_f32_16x16x128_f8f6f4 v[66:69], v[172:179], v[196:203], v[66:69], v235, v235 op_sel_hi:[0,0,0]
	s_setprio 0
	s_barrier
	s_add_i32 s49, s49, s35
	v_lshl_add_u64 v[136:137], s[26:27], 0, v[0:1]
	s_mov_b32 m0, s49
	ds_read_b128 v[180:183], v147 offset:16384
	ds_read_b128 v[184:187], v147 offset:17408
	ds_read_b128 v[188:191], v147 offset:18432
	ds_read_b128 v[192:195], v147 offset:19456
	ds_read_b128 v[196:199], v147 offset:20480
	ds_read_b128 v[200:203], v147 offset:21504
	ds_read_b128 v[204:207], v147 offset:22528
	ds_read_b128 v[208:211], v147 offset:23552
	global_load_lds_dwordx4 v0, s[26:27]
	s_add_i32 m0, s49, 0x2000
	s_add_u32 s50, s26, 0x20000
	v_lshl_add_u64 v[138:139], s[26:27], 0, v[130:131]
	s_addc_u32 s51, s27, 0
	s_add_i32 s49, s52, s35
	global_load_lds_dwordx4 v130, s[26:27]
	s_mov_b32 m0, s49
	v_lshl_add_u64 v[142:143], s[28:29], 0, v[130:131]
	global_load_lds_dwordx4 v0, s[50:51]
	s_add_i32 m0, s49, 0x2000
	s_nop 0
	global_load_lds_dwordx4 v130, s[50:51]
	v_lshl_add_u64 v[140:141], s[28:29], 0, v[0:1]
	s_mov_b32 m0, s23
	s_nop 0
	global_load_lds_dwordx4 v0, s[28:29]
	s_mov_b32 m0, s37
	s_nop 0
	global_load_lds_dwordx4 v130, s[28:29]
	s_waitcnt vmcnt(8)
	s_waitcnt lgkmcnt(0)
	s_barrier
	s_setprio 1
	s_waitcnt lgkmcnt(0)
	v_mfma_scale_f32_16x16x128_f8f6f4 v[62:65], v[148:155], v[180:187], v[62:65], v235, v235 op_sel_hi:[0,0,0]
	v_mfma_scale_f32_16x16x128_f8f6f4 v[58:61], v[156:163], v[180:187], v[58:61], v235, v235 op_sel_hi:[0,0,0]
	v_mfma_scale_f32_16x16x128_f8f6f4 v[46:49], v[148:155], v[188:195], v[46:49], v235, v235 op_sel_hi:[0,0,0]
	v_mfma_scale_f32_16x16x128_f8f6f4 v[42:45], v[156:163], v[188:195], v[42:45], v235, v235 op_sel_hi:[0,0,0]
	v_mfma_scale_f32_16x16x128_f8f6f4 v[30:33], v[148:155], v[196:203], v[30:33], v235, v235 op_sel_hi:[0,0,0]
	v_mfma_scale_f32_16x16x128_f8f6f4 v[26:29], v[156:163], v[196:203], v[26:29], v235, v235 op_sel_hi:[0,0,0]
	v_mfma_scale_f32_16x16x128_f8f6f4 v[14:17], v[148:155], v[204:211], v[14:17], v235, v235 op_sel_hi:[0,0,0]
	v_mfma_scale_f32_16x16x128_f8f6f4 v[10:13], v[156:163], v[204:211], v[10:13], v235, v235 op_sel_hi:[0,0,0]
	s_setprio 0
	s_setprio 1
	v_mfma_scale_f32_16x16x128_f8f6f4 v[54:57], v[164:171], v[180:187], v[54:57], v235, v235 op_sel_hi:[0,0,0]
	v_mfma_scale_f32_16x16x128_f8f6f4 v[50:53], v[172:179], v[180:187], v[50:53], v235, v235 op_sel_hi:[0,0,0]
	v_mfma_scale_f32_16x16x128_f8f6f4 v[38:41], v[164:171], v[188:195], v[38:41], v235, v235 op_sel_hi:[0,0,0]
	v_mfma_scale_f32_16x16x128_f8f6f4 v[34:37], v[172:179], v[188:195], v[34:37], v235, v235 op_sel_hi:[0,0,0]
	v_mfma_scale_f32_16x16x128_f8f6f4 v[22:25], v[164:171], v[196:203], v[22:25], v235, v235 op_sel_hi:[0,0,0]
	v_mfma_scale_f32_16x16x128_f8f6f4 v[18:21], v[172:179], v[196:203], v[18:21], v235, v235 op_sel_hi:[0,0,0]
	v_mfma_scale_f32_16x16x128_f8f6f4 v[6:9], v[164:171], v[204:211], v[6:9], v235, v235 op_sel_hi:[0,0,0]
	v_mfma_scale_f32_16x16x128_f8f6f4 v[2:5], v[172:179], v[204:211], v[2:5], v235, v235 op_sel_hi:[0,0,0]
	s_setprio 0
	s_barrier
; #define PG8_STAGE(bufoff, gbase, voff) do { _Pragma("unroll") for (int _i = 0; _i < 2; ++_i) \
;         __builtin_amdgcn_global_load_lds((const unsigned*)((const char*)(gbase) + (voff)[_i]), (PG8_LAS unsigned*)(lds + (bufoff) + ldsw + _i * 8192), 16, 0, 0); } while (0)
; #define PG8_WAIT_V(n) asm volatile("s_waitcnt vmcnt(" #n ")" ::: "memory")
; #define PG8_WAIT_L(n) asm volatile("s_waitcnt lgkmcnt(" #n ")" ::: "memory")
; #define PG8_BAR __builtin_amdgcn_s_barrier()
; #define PG8_SCHED __builtin_amdgcn_sched_barrier(0)
; #define PG8_STAGEA(bufoff, gbase, h, vsel) do { if constexpr (GATHER) { PG8_STAGE(bufoff, gbase, vsel[h]); } else { PG8_STAGE(bufoff, (gbase) + (h) * hstep, voffA); } } while (0)
; template <class Epi, class Sched, bool ALIGN_EPI = false, bool SP2 = false, bool F8 = false, bool GATHER = false>
; __device__ __forceinline__ void gemm_phase(PG8_LAS unsigned char* lds, const Gemm g, const Sched& S, const Epi& E, const int tid_in) {
;     ...
;             PG8_WAIT_V(8); PG8_WAIT_L(0); PG8_BAR; PG8_MMA(1, 0, At, B0); PG8_MMA(1, 1, At, B1); PG8_BAR; PG8_SCHED;
;             PG8_LDB(B0, 1, 0); PG8_LDB(B1, 1, 1); PG8_SCHED; PG8_LDA(At, 1, 0); PG8_STAGEA(PG8_SA(0, 1), a2, 1, vS);
;             PG8_WAIT_V(8); PG8_WAIT_L(0); PG8_BAR; PG8_MMA(0, 0, At, B0); PG8_MMA(0, 1, At, B1); PG8_BAR; PG8_SCHED;
;             PG8_LDA(At, 1, 1); PG8_STAGE(PG8_SB(1, 0), b3, voffB); PG8_STAGE(PG8_SB(1, 1), b3 + hstep, voffB); PG8_STAGEA(PG8_SA(1, 0), a3, 0, vS);
;             PG8_WAIT_V(8); PG8_WAIT_L(0); PG8_BAR; PG8_MMA(1, 0, At, B0); PG8_MMA(1, 1, At, B1); PG8_BAR; PG8_SCHED;
	s_add_i32 s49, 0, 0x18000
	s_add_i32 s50, 0, 0x1c000
	v_add_u32_e32 v160, s49, v145
	v_add_u32_e32 v176, s50, v145
	ds_read_b128 v[148:151], v160
	ds_read_b128 v[152:155], v160 offset:1024
	ds_read_b128 v[156:159], v160 offset:2048
	ds_read_b128 v[160:163], v160 offset:3072
	ds_read_b128 v[164:167], v176
	ds_read_b128 v[168:171], v176 offset:1024
	ds_read_b128 v[172:175], v176 offset:2048
	ds_read_b128 v[176:179], v176 offset:3072
	s_add_u32 s28, s28, 0x20000
	s_addc_u32 s29, s29, 0
	s_mov_b32 m0, s38
	ds_read_b128 v[180:183], v147 offset:32768
	ds_read_b128 v[184:187], v147 offset:33792
	ds_read_b128 v[188:191], v147 offset:34816
	ds_read_b128 v[192:195], v147 offset:35840
	ds_read_b128 v[196:199], v147 offset:36864
	ds_read_b128 v[200:203], v147 offset:37888
	ds_read_b128 v[204:207], v147 offset:38912
	ds_read_b128 v[208:211], v147 offset:39936
	global_load_lds_dwordx4 v0, s[28:29]
	s_mov_b32 m0, s39
	s_nop 0
	global_load_lds_dwordx4 v130, s[28:29]
	s_waitcnt vmcnt(8)
	s_waitcnt lgkmcnt(0)
	s_barrier
	s_setprio 1
	s_waitcnt lgkmcnt(0)
	v_mfma_scale_f32_16x16x128_f8f6f4 v[126:129], v[148:155], v[180:187], v[126:129], v235, v235 op_sel_hi:[0,0,0]
	v_mfma_scale_f32_16x16x128_f8f6f4 v[122:125], v[156:163], v[180:187], v[122:125], v235, v235 op_sel_hi:[0,0,0]
	v_mfma_scale_f32_16x16x128_f8f6f4 v[110:113], v[148:155], v[188:195], v[110:113], v235, v235 op_sel_hi:[0,0,0]
	v_mfma_scale_f32_16x16x128_f8f6f4 v[106:109], v[156:163], v[188:195], v[106:109], v235, v235 op_sel_hi:[0,0,0]
	v_mfma_scale_f32_16x16x128_f8f6f4 v[94:97], v[148:155], v[196:203], v[94:97], v235, v235 op_sel_hi:[0,0,0]
	v_mfma_scale_f32_16x16x128_f8f6f4 v[90:93], v[156:163], v[196:203], v[90:93], v235, v235 op_sel_hi:[0,0,0]
	v_mfma_scale_f32_16x16x128_f8f6f4 v[78:81], v[148:155], v[204:211], v[78:81], v235, v235 op_sel_hi:[0,0,0]
	v_mfma_scale_f32_16x16x128_f8f6f4 v[74:77], v[156:163], v[204:211], v[74:77], v235, v235 op_sel_hi:[0,0,0]
	s_setprio 0
	s_setprio 1
	v_mfma_scale_f32_16x16x128_f8f6f4 v[118:121], v[164:171], v[180:187], v[118:121], v235, v235 op_sel_hi:[0,0,0]
	v_mfma_scale_f32_16x16x128_f8f6f4 v[114:117], v[172:179], v[180:187], v[114:117], v235, v235 op_sel_hi:[0,0,0]
	v_mfma_scale_f32_16x16x128_f8f6f4 v[102:105], v[164:171], v[188:195], v[102:105], v235, v235 op_sel_hi:[0,0,0]
	v_mfma_scale_f32_16x16x128_f8f6f4 v[98:101], v[172:179], v[188:195], v[98:101], v235, v235 op_sel_hi:[0,0,0]
	v_mfma_scale_f32_16x16x128_f8f6f4 v[86:89], v[164:171], v[196:203], v[86:89], v235, v235 op_sel_hi:[0,0,0]
	v_mfma_scale_f32_16x16x128_f8f6f4 v[82:85], v[172:179], v[196:203], v[82:85], v235, v235 op_sel_hi:[0,0,0]
	v_mfma_scale_f32_16x16x128_f8f6f4 v[70:73], v[164:171], v[204:211], v[70:73], v235, v235 op_sel_hi:[0,0,0]
	v_mfma_scale_f32_16x16x128_f8f6f4 v[66:69], v[172:179], v[204:211], v[66:69], v235, v235 op_sel_hi:[0,0,0]
	s_setprio 0
	s_barrier
	s_add_i32 s28, s49, s35
	v_lshl_add_u64 v[136:137], v[136:137], 0, s[0:1]
	s_mov_b32 m0, s28
	ds_read_b128 v[180:183], v147 offset:49152
	ds_read_b128 v[184:187], v147 offset:50176
	ds_read_b128 v[188:191], v147 offset:51200
	ds_read_b128 v[192:195], v147 offset:52224
	ds_read_b128 v[196:199], v147 offset:53248
	ds_read_b128 v[200:203], v147 offset:54272
	ds_read_b128 v[204:207], v147 offset:55296
	ds_read_b128 v[208:211], v147 offset:56320
	global_load_lds_dwordx4 v[136:137], off
	s_add_i32 m0, s28, 0x2000
	s_add_u32 s26, s26, 0x20080
	v_lshl_add_u64 v[136:137], v[138:139], 0, s[0:1]
	s_addc_u32 s27, s27, 0
	s_add_i32 s28, s50, s35
	global_load_lds_dwordx4 v[136:137], off
	s_mov_b32 m0, s28
	s_nop 0
	global_load_lds_dwordx4 v0, s[26:27]
	s_add_i32 m0, s28, 0x2000
	s_nop 0
	global_load_lds_dwordx4 v130, s[26:27]
	v_lshl_add_u64 v[136:137], v[140:141], 0, s[0:1]
	s_mov_b32 m0, s40
	s_nop 0
	global_load_lds_dwordx4 v[136:137], off
	v_lshl_add_u64 v[136:137], v[142:143], 0, s[0:1]
	s_mov_b32 m0, s41
	s_nop 0
	global_load_lds_dwordx4 v[136:137], off
	s_waitcnt vmcnt(8)
	s_waitcnt lgkmcnt(0)
	s_barrier
	s_setprio 1
	s_waitcnt lgkmcnt(0)
	v_mfma_scale_f32_16x16x128_f8f6f4 v[62:65], v[148:155], v[180:187], v[62:65], v235, v235 op_sel_hi:[0,0,0]
	v_mfma_scale_f32_16x16x128_f8f6f4 v[58:61], v[156:163], v[180:187], v[58:61], v235, v235 op_sel_hi:[0,0,0]
	v_mfma_scale_f32_16x16x128_f8f6f4 v[46:49], v[148:155], v[188:195], v[46:49], v235, v235 op_sel_hi:[0,0,0]
	v_mfma_scale_f32_16x16x128_f8f6f4 v[42:45], v[156:163], v[188:195], v[42:45], v235, v235 op_sel_hi:[0,0,0]
	v_mfma_scale_f32_16x16x128_f8f6f4 v[30:33], v[148:155], v[196:203], v[30:33], v235, v235 op_sel_hi:[0,0,0]
	v_mfma_scale_f32_16x16x128_f8f6f4 v[26:29], v[156:163], v[196:203], v[26:29], v235, v235 op_sel_hi:[0,0,0]
	v_mfma_scale_f32_16x16x128_f8f6f4 v[14:17], v[148:155], v[204:211], v[14:17], v235, v235 op_sel_hi:[0,0,0]
	v_mfma_scale_f32_16x16x128_f8f6f4 v[10:13], v[156:163], v[204:211], v[10:13], v235, v235 op_sel_hi:[0,0,0]
	s_setprio 0
	s_setprio 1
	v_mfma_scale_f32_16x16x128_f8f6f4 v[54:57], v[164:171], v[180:187], v[54:57], v235, v235 op_sel_hi:[0,0,0]
	v_mfma_scale_f32_16x16x128_f8f6f4 v[50:53], v[172:179], v[180:187], v[50:53], v235, v235 op_sel_hi:[0,0,0]
	v_mfma_scale_f32_16x16x128_f8f6f4 v[38:41], v[164:171], v[188:195], v[38:41], v235, v235 op_sel_hi:[0,0,0]
	v_mfma_scale_f32_16x16x128_f8f6f4 v[34:37], v[172:179], v[188:195], v[34:37], v235, v235 op_sel_hi:[0,0,0]
	v_mfma_scale_f32_16x16x128_f8f6f4 v[22:25], v[164:171], v[196:203], v[22:25], v235, v235 op_sel_hi:[0,0,0]
	v_mfma_scale_f32_16x16x128_f8f6f4 v[18:21], v[172:179], v[196:203], v[18:21], v235, v235 op_sel_hi:[0,0,0]
	v_mfma_scale_f32_16x16x128_f8f6f4 v[6:9], v[164:171], v[204:211], v[6:9], v235, v235 op_sel_hi:[0,0,0]
	v_mfma_scale_f32_16x16x128_f8f6f4 v[2:5], v[172:179], v[204:211], v[2:5], v235, v235 op_sel_hi:[0,0,0]
	s_setprio 0
	s_barrier
	s_add_i32 s48, s48, 2
	s_add_u32 s24, s24, 0x100
	s_addc_u32 s25, s25, 0
	s_add_u32 s46, s46, 0x100
	s_addc_u32 s47, s47, 0
	s_cmp_gt_u32 s48, 5
	s_cbranch_scc0 .LBB0_423
	s_and_b64 vcc, exec, s[8:9]
	s_cbranch_vccz .LBB0_426
	s_barrier

; #define PG8_STAGE(bufoff, gbase, voff) do { _Pragma("unroll") for (int _i = 0; _i < 2; ++_i) \
;         __builtin_amdgcn_global_load_lds((const unsigned*)((const char*)(gbase) + (voff)[_i]), (PG8_LAS unsigned*)(lds + (bufoff) + ldsw + _i * 8192), 16, 0, 0); } while (0)
; #define PG8_WAIT_V(n) asm volatile("s_waitcnt vmcnt(" #n ")" ::: "memory")
; #define PG8_WAIT_L(n) asm volatile("s_waitcnt lgkmcnt(" #n ")" ::: "memory")
; #define PG8_BAR __builtin_amdgcn_s_barrier()
; #define PG8_SCHED __builtin_amdgcn_sched_barrier(0)
; #define PG8_STAGEA(bufoff, gbase, h, vsel) do { if constexpr (GATHER) { PG8_STAGE(bufoff, gbase, vsel[h]); } else { PG8_STAGE(bufoff, (gbase) + (h) * hstep, voffA); } } while (0)
; template <class Epi, class Sched, bool ALIGN_EPI = false, bool SP2 = false, bool F8 = false, bool GATHER = false>
; __device__ __forceinline__ void gemm_phase(PG8_LAS unsigned char* lds, const Gemm g, const Sched& S, const Epi& E, const int tid_in) {
;     ...
;             PG8_LDB(B0, 0, 0); PG8_LDB(B1, 0, 1); PG8_SCHED; PG8_LDA(At, 0, 0); PG8_STAGEA(PG8_SA(1, 1), a1, 1, vC);
;             PG8_WAIT_V(8); PG8_WAIT_L(0); PG8_BAR; PG8_MMA(0, 0, At, B0); PG8_MMA(0, 1, At, B1); PG8_BAR; PG8_SCHED;
;             PG8_LDA(At, 0, 1); PG8_STAGE(PG8_SB(0, 0), b2, voffB); PG8_STAGE(PG8_SB(0, 1), b2 + hstep, voffB); PG8_STAGEA(PG8_SA(0, 0), a2, 0, vS);
.LBB0_1160:
	s_add_u32 s28, s26, 0xfffe0080
	s_addc_u32 s29, s27, -1
	s_add_i32 s55, 0, 0x10000
	s_cmp_eq_u32 s53, 4
	s_cselect_b32 s31, s7, s29
	s_cselect_b32 s30, s19, s28
	s_cselect_b32 s29, s21, s52
	s_cselect_b32 s28, s50, s51
	s_add_i32 s60, 0, 0x14000
	v_add_u32_e32 v154, s55, v197
	v_add_u32_e32 v170, s60, v197
	ds_read_b128 v[142:145], v154
	ds_read_b128 v[146:149], v154 offset:1024
	ds_read_b128 v[150:153], v154 offset:2048
	ds_read_b128 v[154:157], v154 offset:3072
	ds_read_b128 v[158:161], v170
	ds_read_b128 v[162:165], v170 offset:1024
	ds_read_b128 v[166:169], v170 offset:2048
	ds_read_b128 v[170:173], v170 offset:3072
	s_add_i32 m0, s41, 0xc000
	ds_read_b128 v[174:177], v199
	ds_read_b128 v[178:181], v199 offset:1024
	ds_read_b128 v[182:185], v199 offset:2048
	ds_read_b128 v[186:189], v199 offset:3072
	ds_read_b128 v[190:193], v199 offset:4096
	ds_read_b128 v[200:203], v199 offset:5120
	ds_read_b128 v[204:207], v199 offset:6144
	ds_read_b128 v[208:211], v199 offset:7168
	global_load_lds_dwordx4 v138, s[26:27]
	s_add_i32 m0, s41, 0xe000
	s_nop 0
	global_load_lds_dwordx4 v140, s[26:27]
	s_waitcnt vmcnt(8)
	s_waitcnt lgkmcnt(0)
	s_barrier
	s_setprio 1
	s_waitcnt lgkmcnt(0)
	v_mfma_f32_16x16x32_bf16 v[126:129], v[142:145], v[174:177], v[126:129]
	v_mfma_f32_16x16x32_bf16 v[122:125], v[150:153], v[174:177], v[122:125]
	v_mfma_f32_16x16x32_bf16 v[110:113], v[142:145], v[182:185], v[110:113]
	v_mfma_f32_16x16x32_bf16 v[106:109], v[150:153], v[182:185], v[106:109]
	v_mfma_f32_16x16x32_bf16 v[94:97], v[142:145], v[190:193], v[94:97]
	v_mfma_f32_16x16x32_bf16 v[90:93], v[150:153], v[190:193], v[90:93]
	v_mfma_f32_16x16x32_bf16 v[78:81], v[142:145], v[204:207], v[78:81]
	v_mfma_f32_16x16x32_bf16 v[74:77], v[150:153], v[204:207], v[74:77]
	v_mfma_f32_16x16x32_bf16 v[126:129], v[146:149], v[178:181], v[126:129]
	v_mfma_f32_16x16x32_bf16 v[122:125], v[154:157], v[178:181], v[122:125]
	v_mfma_f32_16x16x32_bf16 v[110:113], v[146:149], v[186:189], v[110:113]
	v_mfma_f32_16x16x32_bf16 v[106:109], v[154:157], v[186:189], v[106:109]
	v_mfma_f32_16x16x32_bf16 v[94:97], v[146:149], v[200:203], v[94:97]
	v_mfma_f32_16x16x32_bf16 v[90:93], v[154:157], v[200:203], v[90:93]
	v_mfma_f32_16x16x32_bf16 v[78:81], v[146:149], v[208:211], v[78:81]
	v_mfma_f32_16x16x32_bf16 v[74:77], v[154:157], v[208:211], v[74:77]
	s_setprio 0
	s_setprio 1
	v_mfma_f32_16x16x32_bf16 v[118:121], v[158:161], v[174:177], v[118:121]
	v_mfma_f32_16x16x32_bf16 v[114:117], v[166:169], v[174:177], v[114:117]
	v_mfma_f32_16x16x32_bf16 v[102:105], v[158:161], v[182:185], v[102:105]
	v_mfma_f32_16x16x32_bf16 v[98:101], v[166:169], v[182:185], v[98:101]
	v_mfma_f32_16x16x32_bf16 v[86:89], v[158:161], v[190:193], v[86:89]
	v_mfma_f32_16x16x32_bf16 v[82:85], v[166:169], v[190:193], v[82:85]
	v_mfma_f32_16x16x32_bf16 v[70:73], v[158:161], v[204:207], v[70:73]
	v_mfma_f32_16x16x32_bf16 v[66:69], v[166:169], v[204:207], v[66:69]
	v_mfma_f32_16x16x32_bf16 v[118:121], v[162:165], v[178:181], v[118:121]
	v_mfma_f32_16x16x32_bf16 v[114:117], v[170:173], v[178:181], v[114:117]
	v_mfma_f32_16x16x32_bf16 v[102:105], v[162:165], v[186:189], v[102:105]
	v_mfma_f32_16x16x32_bf16 v[98:101], v[170:173], v[186:189], v[98:101]
	v_mfma_f32_16x16x32_bf16 v[86:89], v[162:165], v[200:203], v[86:89]
	v_mfma_f32_16x16x32_bf16 v[82:85], v[170:173], v[200:203], v[82:85]
	v_mfma_f32_16x16x32_bf16 v[70:73], v[162:165], v[208:211], v[70:73]
	v_mfma_f32_16x16x32_bf16 v[66:69], v[170:173], v[208:211], v[66:69]
	s_setprio 0
	s_barrier
	s_add_i32 s55, s55, s40
	v_lshl_add_u64 v[194:195], s[28:29], 0, v[0:1]
	s_mov_b32 m0, s55
	ds_read_b128 v[174:177], v199 offset:16384
	ds_read_b128 v[178:181], v199 offset:17408
	ds_read_b128 v[182:185], v199 offset:18432
	ds_read_b128 v[186:189], v199 offset:19456
	ds_read_b128 v[190:193], v199 offset:20480
	ds_read_b128 v[200:203], v199 offset:21504
	ds_read_b128 v[204:207], v199 offset:22528
	ds_read_b128 v[208:211], v199 offset:23552
	global_load_lds_dwordx4 v0, s[28:29]
	s_add_i32 m0, s55, 0x2000
	s_add_u32 s56, s28, 0x20000
	v_lshl_add_u64 v[212:213], s[28:29], 0, v[134:135]
	s_addc_u32 s57, s29, 0
	s_add_i32 s55, s60, s40
	global_load_lds_dwordx4 v134, s[28:29]
	s_mov_b32 m0, s55
	v_lshl_add_u64 v[216:217], s[30:31], 0, v[132:133]
	global_load_lds_dwordx4 v0, s[56:57]
	s_add_i32 m0, s55, 0x2000
	s_nop 0
	global_load_lds_dwordx4 v134, s[56:57]
	v_lshl_add_u64 v[214:215], s[30:31], 0, v[130:131]
	s_mov_b32 m0, s41
	s_nop 0
	global_load_lds_dwordx4 v130, s[30:31]
	s_mov_b32 m0, s42
	s_nop 0
	global_load_lds_dwordx4 v132, s[30:31]
	s_waitcnt vmcnt(8)
	s_waitcnt lgkmcnt(0)
	s_barrier
; #define PG8_WAIT_V(n) asm volatile("s_waitcnt vmcnt(" #n ")" ::: "memory")
; #define PG8_WAIT_L(n) asm volatile("s_waitcnt lgkmcnt(" #n ")" ::: "memory")
; #define PG8_BAR __builtin_amdgcn_s_barrier()
; #define PG8_SCHED __builtin_amdgcn_sched_barrier(0)
; #define PG8_STAGEA(bufoff, gbase, h, vsel) do { if constexpr (GATHER) { PG8_STAGE(bufoff, gbase, vsel[h]); } else { PG8_STAGE(bufoff, (gbase) + (h) * hstep, voffA); } } while (0)
; template <class Epi, class Sched, bool ALIGN_EPI = false, bool SP2 = false, bool F8 = false, bool GATHER = false>
; __device__ __forceinline__ void gemm_phase(PG8_LAS unsigned char* lds, const Gemm g, const Sched& S, const Epi& E, const int tid_in) {
;     ...
;             PG8_WAIT_V(8); PG8_WAIT_L(0); PG8_BAR; PG8_MMA(1, 0, At, B0); PG8_MMA(1, 1, At, B1); PG8_BAR; PG8_SCHED;
;             PG8_LDB(B0, 1, 0); PG8_LDB(B1, 1, 1); PG8_SCHED; PG8_LDA(At, 1, 0); PG8_STAGEA(PG8_SA(0, 1), a2, 1, vS);
;             PG8_WAIT_V(8); PG8_WAIT_L(0); PG8_BAR; PG8_MMA(0, 0, At, B0); PG8_MMA(0, 1, At, B1); PG8_BAR; PG8_SCHED;
	s_setprio 1
	s_waitcnt lgkmcnt(0)
	v_mfma_f32_16x16x32_bf16 v[62:65], v[142:145], v[174:177], v[62:65]
	v_mfma_f32_16x16x32_bf16 v[58:61], v[150:153], v[174:177], v[58:61]
	v_mfma_f32_16x16x32_bf16 v[46:49], v[142:145], v[182:185], v[46:49]
	v_mfma_f32_16x16x32_bf16 v[42:45], v[150:153], v[182:185], v[42:45]
	v_mfma_f32_16x16x32_bf16 v[30:33], v[142:145], v[190:193], v[30:33]
	v_mfma_f32_16x16x32_bf16 v[26:29], v[150:153], v[190:193], v[26:29]
	v_mfma_f32_16x16x32_bf16 v[14:17], v[142:145], v[204:207], v[14:17]
	v_mfma_f32_16x16x32_bf16 v[10:13], v[150:153], v[204:207], v[10:13]
	v_mfma_f32_16x16x32_bf16 v[62:65], v[146:149], v[178:181], v[62:65]
	v_mfma_f32_16x16x32_bf16 v[58:61], v[154:157], v[178:181], v[58:61]
	v_mfma_f32_16x16x32_bf16 v[46:49], v[146:149], v[186:189], v[46:49]
	v_mfma_f32_16x16x32_bf16 v[42:45], v[154:157], v[186:189], v[42:45]
	v_mfma_f32_16x16x32_bf16 v[30:33], v[146:149], v[200:203], v[30:33]
	v_mfma_f32_16x16x32_bf16 v[26:29], v[154:157], v[200:203], v[26:29]
	v_mfma_f32_16x16x32_bf16 v[14:17], v[146:149], v[208:211], v[14:17]
	v_mfma_f32_16x16x32_bf16 v[10:13], v[154:157], v[208:211], v[10:13]
	s_setprio 0
	s_setprio 1
	v_mfma_f32_16x16x32_bf16 v[54:57], v[158:161], v[174:177], v[54:57]
	v_mfma_f32_16x16x32_bf16 v[50:53], v[166:169], v[174:177], v[50:53]
	v_mfma_f32_16x16x32_bf16 v[38:41], v[158:161], v[182:185], v[38:41]
	v_mfma_f32_16x16x32_bf16 v[34:37], v[166:169], v[182:185], v[34:37]
	v_mfma_f32_16x16x32_bf16 v[22:25], v[158:161], v[190:193], v[22:25]
	v_mfma_f32_16x16x32_bf16 v[18:21], v[166:169], v[190:193], v[18:21]
	v_mfma_f32_16x16x32_bf16 v[6:9], v[158:161], v[204:207], v[6:9]
	v_mfma_f32_16x16x32_bf16 v[2:5], v[166:169], v[204:207], v[2:5]
	v_mfma_f32_16x16x32_bf16 v[54:57], v[162:165], v[178:181], v[54:57]
	v_mfma_f32_16x16x32_bf16 v[50:53], v[170:173], v[178:181], v[50:53]
	v_mfma_f32_16x16x32_bf16 v[38:41], v[162:165], v[186:189], v[38:41]
	v_mfma_f32_16x16x32_bf16 v[34:37], v[170:173], v[186:189], v[34:37]
	v_mfma_f32_16x16x32_bf16 v[22:25], v[162:165], v[200:203], v[22:25]
	v_mfma_f32_16x16x32_bf16 v[18:21], v[170:173], v[200:203], v[18:21]
	v_mfma_f32_16x16x32_bf16 v[6:9], v[162:165], v[208:211], v[6:9]
	v_mfma_f32_16x16x32_bf16 v[2:5], v[170:173], v[208:211], v[2:5]
	s_setprio 0
	s_barrier
	s_add_i32 s55, 0, 0x18000
	s_add_i32 s56, 0, 0x1c000
	v_add_u32_e32 v154, s55, v197
	v_add_u32_e32 v170, s56, v197
	ds_read_b128 v[142:145], v154
	ds_read_b128 v[146:149], v154 offset:1024
	ds_read_b128 v[150:153], v154 offset:2048
	ds_read_b128 v[154:157], v154 offset:3072
	ds_read_b128 v[158:161], v170
	ds_read_b128 v[162:165], v170 offset:1024
	ds_read_b128 v[166:169], v170 offset:2048
	ds_read_b128 v[170:173], v170 offset:3072
	s_add_u32 s30, s30, 0x20000
	s_addc_u32 s31, s31, 0
	s_mov_b32 m0, s43
	ds_read_b128 v[174:177], v199 offset:32768
	ds_read_b128 v[178:181], v199 offset:33792
	ds_read_b128 v[182:185], v199 offset:34816
	ds_read_b128 v[186:189], v199 offset:35840
	ds_read_b128 v[190:193], v199 offset:36864
	ds_read_b128 v[200:203], v199 offset:37888
	ds_read_b128 v[204:207], v199 offset:38912
	ds_read_b128 v[208:211], v199 offset:39936
	global_load_lds_dwordx4 v130, s[30:31]
	s_mov_b32 m0, s44
	s_nop 0
	global_load_lds_dwordx4 v132, s[30:31]
	s_waitcnt vmcnt(8)
	s_waitcnt lgkmcnt(0)
	s_barrier
	s_setprio 1
	s_waitcnt lgkmcnt(0)
	v_mfma_f32_16x16x32_bf16 v[126:129], v[142:145], v[174:177], v[126:129]
	v_mfma_f32_16x16x32_bf16 v[122:125], v[150:153], v[174:177], v[122:125]
	v_mfma_f32_16x16x32_bf16 v[110:113], v[142:145], v[182:185], v[110:113]
	v_mfma_f32_16x16x32_bf16 v[106:109], v[150:153], v[182:185], v[106:109]
	v_mfma_f32_16x16x32_bf16 v[94:97], v[142:145], v[190:193], v[94:97]
	v_mfma_f32_16x16x32_bf16 v[90:93], v[150:153], v[190:193], v[90:93]
	v_mfma_f32_16x16x32_bf16 v[78:81], v[142:145], v[204:207], v[78:81]
	v_mfma_f32_16x16x32_bf16 v[74:77], v[150:153], v[204:207], v[74:77]
	v_mfma_f32_16x16x32_bf16 v[126:129], v[146:149], v[178:181], v[126:129]
	v_mfma_f32_16x16x32_bf16 v[122:125], v[154:157], v[178:181], v[122:125]
	v_mfma_f32_16x16x32_bf16 v[110:113], v[146:149], v[186:189], v[110:113]
	v_mfma_f32_16x16x32_bf16 v[106:109], v[154:157], v[186:189], v[106:109]
	v_mfma_f32_16x16x32_bf16 v[94:97], v[146:149], v[200:203], v[94:97]
	v_mfma_f32_16x16x32_bf16 v[90:93], v[154:157], v[200:203], v[90:93]
	v_mfma_f32_16x16x32_bf16 v[78:81], v[146:149], v[208:211], v[78:81]
	v_mfma_f32_16x16x32_bf16 v[74:77], v[154:157], v[208:211], v[74:77]
	s_setprio 0
	s_setprio 1
	v_mfma_f32_16x16x32_bf16 v[118:121], v[158:161], v[174:177], v[118:121]
	v_mfma_f32_16x16x32_bf16 v[114:117], v[166:169], v[174:177], v[114:117]
	v_mfma_f32_16x16x32_bf16 v[102:105], v[158:161], v[182:185], v[102:105]
	v_mfma_f32_16x16x32_bf16 v[98:101], v[166:169], v[182:185], v[98:101]
	v_mfma_f32_16x16x32_bf16 v[86:89], v[158:161], v[190:193], v[86:89]
	v_mfma_f32_16x16x32_bf16 v[82:85], v[166:169], v[190:193], v[82:85]
	v_mfma_f32_16x16x32_bf16 v[70:73], v[158:161], v[204:207], v[70:73]
	v_mfma_f32_16x16x32_bf16 v[66:69], v[166:169], v[204:207], v[66:69]
	v_mfma_f32_16x16x32_bf16 v[118:121], v[162:165], v[178:181], v[118:121]
	v_mfma_f32_16x16x32_bf16 v[114:117], v[170:173], v[178:181], v[114:117]
	v_mfma_f32_16x16x32_bf16 v[102:105], v[162:165], v[186:189], v[102:105]
	v_mfma_f32_16x16x32_bf16 v[98:101], v[170:173], v[186:189], v[98:101]
	v_mfma_f32_16x16x32_bf16 v[86:89], v[162:165], v[200:203], v[86:89]
	v_mfma_f32_16x16x32_bf16 v[82:85], v[170:173], v[200:203], v[82:85]
	v_mfma_f32_16x16x32_bf16 v[70:73], v[162:165], v[208:211], v[70:73]
	v_mfma_f32_16x16x32_bf16 v[66:69], v[170:173], v[208:211], v[66:69]
	s_setprio 0
	s_barrier
; #define PG8_STAGE(bufoff, gbase, voff) do { _Pragma("unroll") for (int _i = 0; _i < 2; ++_i) \
;         __builtin_amdgcn_global_load_lds((const unsigned*)((const char*)(gbase) + (voff)[_i]), (PG8_LAS unsigned*)(lds + (bufoff) + ldsw + _i * 8192), 16, 0, 0); } while (0)
; #define PG8_WAIT_V(n) asm volatile("s_waitcnt vmcnt(" #n ")" ::: "memory")
; #define PG8_WAIT_L(n) asm volatile("s_waitcnt lgkmcnt(" #n ")" ::: "memory")
; #define PG8_BAR __builtin_amdgcn_s_barrier()
; #define PG8_SCHED __builtin_amdgcn_sched_barrier(0)
; #define PG8_STAGEA(bufoff, gbase, h, vsel) do { if constexpr (GATHER) { PG8_STAGE(bufoff, gbase, vsel[h]); } else { PG8_STAGE(bufoff, (gbase) + (h) * hstep, voffA); } } while (0)
; template <class Epi, class Sched, bool ALIGN_EPI = false, bool SP2 = false, bool F8 = false, bool GATHER = false>
; __device__ __forceinline__ void gemm_phase(PG8_LAS unsigned char* lds, const Gemm g, const Sched& S, const Epi& E, const int tid_in) {
;     ...
;         for (int t = 0; t < nt; t += 2) {
;             const bool last = (t == nt - 2);
;             const char* a1 = cA + (size_t)(t + 1) * kstep;
;             const char* a2 = last ? nA : cA + (size_t)(t + 2) * kstep; const char* b2 = last ? nB : cB + (size_t)(t + 2) * kstep;
;             const char* a3 = a2 + kstep; const char* b3 = b2 + kstep;
;     ...
;             PG8_LDA(At, 1, 1); PG8_STAGE(PG8_SB(1, 0), b3, voffB); PG8_STAGE(PG8_SB(1, 1), b3 + hstep, voffB); PG8_STAGEA(PG8_SA(1, 0), a3, 0, vS);
;             PG8_WAIT_V(8); PG8_WAIT_L(0); PG8_BAR; PG8_MMA(1, 0, At, B0); PG8_MMA(1, 1, At, B1); PG8_BAR; PG8_SCHED;
	s_add_i32 s30, s55, s40
	v_lshl_add_u64 v[194:195], v[194:195], 0, s[0:1]
	s_mov_b32 m0, s30
	ds_read_b128 v[174:177], v199 offset:49152
	ds_read_b128 v[178:181], v199 offset:50176
	ds_read_b128 v[182:185], v199 offset:51200
	ds_read_b128 v[186:189], v199 offset:52224
	ds_read_b128 v[190:193], v199 offset:53248
	ds_read_b128 v[200:203], v199 offset:54272
	ds_read_b128 v[204:207], v199 offset:55296
	ds_read_b128 v[208:211], v199 offset:56320
	global_load_lds_dwordx4 v[194:195], off
	s_add_i32 m0, s30, 0x2000
	s_add_u32 s28, s28, 0x20080
	v_lshl_add_u64 v[194:195], v[212:213], 0, s[0:1]
	s_addc_u32 s29, s29, 0
	s_add_i32 s30, s56, s40
	global_load_lds_dwordx4 v[194:195], off
	s_mov_b32 m0, s30
	s_nop 0
	global_load_lds_dwordx4 v0, s[28:29]
	s_add_i32 m0, s30, 0x2000
	s_nop 0
	global_load_lds_dwordx4 v134, s[28:29]
	v_lshl_add_u64 v[194:195], v[214:215], 0, s[0:1]
	s_mov_b32 m0, s45
	s_nop 0
	global_load_lds_dwordx4 v[194:195], off
	v_lshl_add_u64 v[194:195], v[216:217], 0, s[0:1]
	s_mov_b32 m0, s46
	s_nop 0
	global_load_lds_dwordx4 v[194:195], off
	s_waitcnt vmcnt(8)
	s_waitcnt lgkmcnt(0)
	s_barrier
	s_setprio 1
	s_waitcnt lgkmcnt(0)
	v_mfma_f32_16x16x32_bf16 v[62:65], v[142:145], v[174:177], v[62:65]
	v_mfma_f32_16x16x32_bf16 v[58:61], v[150:153], v[174:177], v[58:61]
	v_mfma_f32_16x16x32_bf16 v[46:49], v[142:145], v[182:185], v[46:49]
	v_mfma_f32_16x16x32_bf16 v[42:45], v[150:153], v[182:185], v[42:45]
	v_mfma_f32_16x16x32_bf16 v[30:33], v[142:145], v[190:193], v[30:33]
	v_mfma_f32_16x16x32_bf16 v[26:29], v[150:153], v[190:193], v[26:29]
	v_mfma_f32_16x16x32_bf16 v[14:17], v[142:145], v[204:207], v[14:17]
	v_mfma_f32_16x16x32_bf16 v[10:13], v[150:153], v[204:207], v[10:13]
	v_mfma_f32_16x16x32_bf16 v[62:65], v[146:149], v[178:181], v[62:65]
	v_mfma_f32_16x16x32_bf16 v[58:61], v[154:157], v[178:181], v[58:61]
	v_mfma_f32_16x16x32_bf16 v[46:49], v[146:149], v[186:189], v[46:49]
	v_mfma_f32_16x16x32_bf16 v[42:45], v[154:157], v[186:189], v[42:45]
	v_mfma_f32_16x16x32_bf16 v[30:33], v[146:149], v[200:203], v[30:33]
	v_mfma_f32_16x16x32_bf16 v[26:29], v[154:157], v[200:203], v[26:29]
	v_mfma_f32_16x16x32_bf16 v[14:17], v[146:149], v[208:211], v[14:17]
	v_mfma_f32_16x16x32_bf16 v[10:13], v[154:157], v[208:211], v[10:13]
	s_setprio 0
	s_setprio 1
	v_mfma_f32_16x16x32_bf16 v[54:57], v[158:161], v[174:177], v[54:57]
	v_mfma_f32_16x16x32_bf16 v[50:53], v[166:169], v[174:177], v[50:53]
	v_mfma_f32_16x16x32_bf16 v[38:41], v[158:161], v[182:185], v[38:41]
	v_mfma_f32_16x16x32_bf16 v[34:37], v[166:169], v[182:185], v[34:37]
	v_mfma_f32_16x16x32_bf16 v[22:25], v[158:161], v[190:193], v[22:25]
	v_mfma_f32_16x16x32_bf16 v[18:21], v[166:169], v[190:193], v[18:21]
	v_mfma_f32_16x16x32_bf16 v[6:9], v[158:161], v[204:207], v[6:9]
	v_mfma_f32_16x16x32_bf16 v[2:5], v[166:169], v[204:207], v[2:5]
	v_mfma_f32_16x16x32_bf16 v[54:57], v[162:165], v[178:181], v[54:57]
	v_mfma_f32_16x16x32_bf16 v[50:53], v[170:173], v[178:181], v[50:53]
	v_mfma_f32_16x16x32_bf16 v[38:41], v[162:165], v[186:189], v[38:41]
	v_mfma_f32_16x16x32_bf16 v[34:37], v[170:173], v[186:189], v[34:37]
	v_mfma_f32_16x16x32_bf16 v[22:25], v[162:165], v[200:203], v[22:25]
	v_mfma_f32_16x16x32_bf16 v[18:21], v[170:173], v[200:203], v[18:21]
	v_mfma_f32_16x16x32_bf16 v[6:9], v[162:165], v[208:211], v[6:9]
	v_mfma_f32_16x16x32_bf16 v[2:5], v[170:173], v[208:211], v[2:5]
	s_setprio 0
	s_barrier
	s_add_i32 s53, s53, 2
	s_add_u32 s26, s26, 0x100
	s_addc_u32 s27, s27, 0
	s_add_u32 s51, s51, 0x100
	s_addc_u32 s52, s52, 0
	s_cmp_gt_u32 s53, 5
	s_cbranch_scc0 .LBB0_1160
	s_and_b64 vcc, exec, s[16:17]
	s_cbranch_vccz .LBB0_1163
	s_barrier

; #define PG8_STAGE(bufoff, gbase, voff) do { _Pragma("unroll") for (int _i = 0; _i < 2; ++_i) \
;         __builtin_amdgcn_global_load_lds((const unsigned*)((const char*)(gbase) + (voff)[_i]), (PG8_LAS unsigned*)(lds + (bufoff) + ldsw + _i * 8192), 16, 0, 0); } while (0)
; #define PG8_WAIT_V(n) asm volatile("s_waitcnt vmcnt(" #n ")" ::: "memory")
; #define PG8_WAIT_L(n) asm volatile("s_waitcnt lgkmcnt(" #n ")" ::: "memory")
; #define PG8_BAR __builtin_amdgcn_s_barrier()
; #define PG8_SCHED __builtin_amdgcn_sched_barrier(0)
; #define PG8_STAGEA(bufoff, gbase, h, vsel) do { if constexpr (GATHER) { PG8_STAGE(bufoff, gbase, vsel[h]); } else { PG8_STAGE(bufoff, (gbase) + (h) * hstep, voffA); } } while (0)
; template <class Epi, class Sched, bool ALIGN_EPI = false, bool SP2 = false, bool F8 = false, bool GATHER = false>
; __device__ __forceinline__ void gemm_phase(PG8_LAS unsigned char* lds, const Gemm g, const Sched& S, const Epi& E, const int tid_in) {
;     ...
;             PG8_LDB(B0, 0, 0); PG8_LDB(B1, 0, 1); PG8_SCHED; PG8_LDA(At, 0, 0); PG8_STAGEA(PG8_SA(1, 1), a1, 1, vC);
;             PG8_WAIT_V(8); PG8_WAIT_L(0); PG8_BAR; PG8_MMA(0, 0, At, B0); PG8_MMA(0, 1, At, B1); PG8_BAR; PG8_SCHED;
;             PG8_LDA(At, 0, 1); PG8_STAGE(PG8_SB(0, 0), b2, voffB); PG8_STAGE(PG8_SB(0, 1), b2 + hstep, voffB); PG8_STAGEA(PG8_SA(0, 0), a2, 0, vS);
.LBB0_1324:
	s_add_u32 s24, s22, 0xfffc0080
	s_addc_u32 s25, s23, -1
	s_add_i32 s49, 0, 0x10000
	s_cmp_eq_u32 s48, 12
	s_cselect_b32 s27, s17, s25
	s_cselect_b32 s26, s44, s24
	s_cselect_b32 s25, s15, s47
	s_cselect_b32 s24, s45, s46
	s_add_i32 s52, 0, 0x14000
	v_add_u32_e32 v156, s49, v141
	v_add_u32_e32 v172, s52, v141
	ds_read_b128 v[144:147], v156
	ds_read_b128 v[148:151], v156 offset:1024
	ds_read_b128 v[152:155], v156 offset:2048
	ds_read_b128 v[156:159], v156 offset:3072
	ds_read_b128 v[160:163], v172
	ds_read_b128 v[164:167], v172 offset:1024
	ds_read_b128 v[168:171], v172 offset:2048
	ds_read_b128 v[172:175], v172 offset:3072
	s_add_i32 m0, s11, 0xc000
	ds_read_b128 v[176:179], v143
	ds_read_b128 v[180:183], v143 offset:1024
	ds_read_b128 v[184:187], v143 offset:2048
	ds_read_b128 v[188:191], v143 offset:3072
	ds_read_b128 v[192:195], v143 offset:4096
	ds_read_b128 v[196:199], v143 offset:5120
	ds_read_b128 v[200:203], v143 offset:6144
	ds_read_b128 v[204:207], v143 offset:7168
	global_load_lds_dwordx4 v136, s[22:23]
	s_add_i32 m0, s11, 0xe000
	s_nop 0
	global_load_lds_dwordx4 v138, s[22:23]
	s_waitcnt vmcnt(8)
	s_waitcnt lgkmcnt(0)
	s_barrier
	s_setprio 1
	s_waitcnt lgkmcnt(0)
	v_mfma_f32_16x16x32_bf16 v[126:129], v[144:147], v[176:179], v[126:129]
	v_mfma_f32_16x16x32_bf16 v[122:125], v[152:155], v[176:179], v[122:125]
	v_mfma_f32_16x16x32_bf16 v[118:121], v[144:147], v[184:187], v[118:121]
	v_mfma_f32_16x16x32_bf16 v[114:117], v[152:155], v[184:187], v[114:117]
	v_mfma_f32_16x16x32_bf16 v[102:105], v[144:147], v[192:195], v[102:105]
	v_mfma_f32_16x16x32_bf16 v[98:101], v[152:155], v[192:195], v[98:101]
	v_mfma_f32_16x16x32_bf16 v[86:89], v[144:147], v[200:203], v[86:89]
	v_mfma_f32_16x16x32_bf16 v[82:85], v[152:155], v[200:203], v[82:85]
	v_mfma_f32_16x16x32_bf16 v[126:129], v[148:151], v[180:183], v[126:129]
	v_mfma_f32_16x16x32_bf16 v[122:125], v[156:159], v[180:183], v[122:125]
	v_mfma_f32_16x16x32_bf16 v[118:121], v[148:151], v[188:191], v[118:121]
	v_mfma_f32_16x16x32_bf16 v[114:117], v[156:159], v[188:191], v[114:117]
	v_mfma_f32_16x16x32_bf16 v[102:105], v[148:151], v[196:199], v[102:105]
	v_mfma_f32_16x16x32_bf16 v[98:101], v[156:159], v[196:199], v[98:101]
	v_mfma_f32_16x16x32_bf16 v[86:89], v[148:151], v[204:207], v[86:89]
	v_mfma_f32_16x16x32_bf16 v[82:85], v[156:159], v[204:207], v[82:85]
	s_setprio 0
	s_setprio 1
	v_mfma_f32_16x16x32_bf16 v[110:113], v[160:163], v[176:179], v[110:113]
	v_mfma_f32_16x16x32_bf16 v[106:109], v[168:171], v[176:179], v[106:109]
	v_mfma_f32_16x16x32_bf16 v[94:97], v[160:163], v[184:187], v[94:97]
	v_mfma_f32_16x16x32_bf16 v[90:93], v[168:171], v[184:187], v[90:93]
	v_mfma_f32_16x16x32_bf16 v[78:81], v[160:163], v[192:195], v[78:81]
	v_mfma_f32_16x16x32_bf16 v[74:77], v[168:171], v[192:195], v[74:77]
	v_mfma_f32_16x16x32_bf16 v[70:73], v[160:163], v[200:203], v[70:73]
	v_mfma_f32_16x16x32_bf16 v[66:69], v[168:171], v[200:203], v[66:69]
	v_mfma_f32_16x16x32_bf16 v[110:113], v[164:167], v[180:183], v[110:113]
	v_mfma_f32_16x16x32_bf16 v[106:109], v[172:175], v[180:183], v[106:109]
	v_mfma_f32_16x16x32_bf16 v[94:97], v[164:167], v[188:191], v[94:97]
	v_mfma_f32_16x16x32_bf16 v[90:93], v[172:175], v[188:191], v[90:93]
	v_mfma_f32_16x16x32_bf16 v[78:81], v[164:167], v[196:199], v[78:81]
	v_mfma_f32_16x16x32_bf16 v[74:77], v[172:175], v[196:199], v[74:77]
	v_mfma_f32_16x16x32_bf16 v[70:73], v[164:167], v[204:207], v[70:73]
	v_mfma_f32_16x16x32_bf16 v[66:69], v[172:175], v[204:207], v[66:69]
	s_setprio 0
	s_barrier
	s_add_i32 s49, s49, s35
	v_lshl_add_u64 v[208:209], s[24:25], 0, v[0:1]
	s_mov_b32 m0, s49
	ds_read_b128 v[176:179], v143 offset:16384
	ds_read_b128 v[180:183], v143 offset:17408
	ds_read_b128 v[184:187], v143 offset:18432
	ds_read_b128 v[188:191], v143 offset:19456
	ds_read_b128 v[192:195], v143 offset:20480
	ds_read_b128 v[196:199], v143 offset:21504
	ds_read_b128 v[200:203], v143 offset:22528
	ds_read_b128 v[204:207], v143 offset:23552
	global_load_lds_dwordx4 v0, s[24:25]
	s_add_i32 m0, s49, 0x2000
	s_add_u32 s50, s24, 0x40000
	v_lshl_add_u64 v[210:211], s[24:25], 0, v[130:131]
	s_addc_u32 s51, s25, 0
	s_add_i32 s49, s52, s35
	global_load_lds_dwordx4 v130, s[24:25]
	s_mov_b32 m0, s49
	v_lshl_add_u64 v[214:215], s[26:27], 0, v[132:133]
	global_load_lds_dwordx4 v0, s[50:51]
	s_add_i32 m0, s49, 0x2000
	s_nop 0
	global_load_lds_dwordx4 v130, s[50:51]
	v_lshl_add_u64 v[212:213], s[26:27], 0, v[134:135]
	s_mov_b32 m0, s11
	s_nop 0
	global_load_lds_dwordx4 v134, s[26:27]
	s_mov_b32 m0, s13
	s_nop 0
	global_load_lds_dwordx4 v132, s[26:27]
	s_waitcnt vmcnt(8)
	s_waitcnt lgkmcnt(0)
	s_barrier
; #define PG8_WAIT_V(n) asm volatile("s_waitcnt vmcnt(" #n ")" ::: "memory")
; #define PG8_WAIT_L(n) asm volatile("s_waitcnt lgkmcnt(" #n ")" ::: "memory")
; #define PG8_BAR __builtin_amdgcn_s_barrier()
; #define PG8_SCHED __builtin_amdgcn_sched_barrier(0)
; #define PG8_STAGEA(bufoff, gbase, h, vsel) do { if constexpr (GATHER) { PG8_STAGE(bufoff, gbase, vsel[h]); } else { PG8_STAGE(bufoff, (gbase) + (h) * hstep, voffA); } } while (0)
; template <class Epi, class Sched, bool ALIGN_EPI = false, bool SP2 = false, bool F8 = false, bool GATHER = false>
; __device__ __forceinline__ void gemm_phase(PG8_LAS unsigned char* lds, const Gemm g, const Sched& S, const Epi& E, const int tid_in) {
;     ...
;             PG8_WAIT_V(8); PG8_WAIT_L(0); PG8_BAR; PG8_MMA(1, 0, At, B0); PG8_MMA(1, 1, At, B1); PG8_BAR; PG8_SCHED;
;             PG8_LDB(B0, 1, 0); PG8_LDB(B1, 1, 1); PG8_SCHED; PG8_LDA(At, 1, 0); PG8_STAGEA(PG8_SA(0, 1), a2, 1, vS);
;             PG8_WAIT_V(8); PG8_WAIT_L(0); PG8_BAR; PG8_MMA(0, 0, At, B0); PG8_MMA(0, 1, At, B1); PG8_BAR; PG8_SCHED;
	s_setprio 1
	s_waitcnt lgkmcnt(0)
	v_mfma_f32_16x16x32_bf16 v[62:65], v[144:147], v[176:179], v[62:65]
	v_mfma_f32_16x16x32_bf16 v[58:61], v[152:155], v[176:179], v[58:61]
	v_mfma_f32_16x16x32_bf16 v[54:57], v[144:147], v[184:187], v[54:57]
	v_mfma_f32_16x16x32_bf16 v[50:53], v[152:155], v[184:187], v[50:53]
	v_mfma_f32_16x16x32_bf16 v[38:41], v[144:147], v[192:195], v[38:41]
	v_mfma_f32_16x16x32_bf16 v[34:37], v[152:155], v[192:195], v[34:37]
	v_mfma_f32_16x16x32_bf16 v[22:25], v[144:147], v[200:203], v[22:25]
	v_mfma_f32_16x16x32_bf16 v[18:21], v[152:155], v[200:203], v[18:21]
	v_mfma_f32_16x16x32_bf16 v[62:65], v[148:151], v[180:183], v[62:65]
	v_mfma_f32_16x16x32_bf16 v[58:61], v[156:159], v[180:183], v[58:61]
	v_mfma_f32_16x16x32_bf16 v[54:57], v[148:151], v[188:191], v[54:57]
	v_mfma_f32_16x16x32_bf16 v[50:53], v[156:159], v[188:191], v[50:53]
	v_mfma_f32_16x16x32_bf16 v[38:41], v[148:151], v[196:199], v[38:41]
	v_mfma_f32_16x16x32_bf16 v[34:37], v[156:159], v[196:199], v[34:37]
	v_mfma_f32_16x16x32_bf16 v[22:25], v[148:151], v[204:207], v[22:25]
	v_mfma_f32_16x16x32_bf16 v[18:21], v[156:159], v[204:207], v[18:21]
	s_setprio 0
	s_setprio 1
	v_mfma_f32_16x16x32_bf16 v[46:49], v[160:163], v[176:179], v[46:49]
	v_mfma_f32_16x16x32_bf16 v[42:45], v[168:171], v[176:179], v[42:45]
	v_mfma_f32_16x16x32_bf16 v[30:33], v[160:163], v[184:187], v[30:33]
	v_mfma_f32_16x16x32_bf16 v[26:29], v[168:171], v[184:187], v[26:29]
	v_mfma_f32_16x16x32_bf16 v[14:17], v[160:163], v[192:195], v[14:17]
	v_mfma_f32_16x16x32_bf16 v[10:13], v[168:171], v[192:195], v[10:13]
	v_mfma_f32_16x16x32_bf16 v[6:9], v[160:163], v[200:203], v[6:9]
	v_mfma_f32_16x16x32_bf16 v[2:5], v[168:171], v[200:203], v[2:5]
	v_mfma_f32_16x16x32_bf16 v[46:49], v[164:167], v[180:183], v[46:49]
	v_mfma_f32_16x16x32_bf16 v[42:45], v[172:175], v[180:183], v[42:45]
	v_mfma_f32_16x16x32_bf16 v[30:33], v[164:167], v[188:191], v[30:33]
	v_mfma_f32_16x16x32_bf16 v[26:29], v[172:175], v[188:191], v[26:29]
	v_mfma_f32_16x16x32_bf16 v[14:17], v[164:167], v[196:199], v[14:17]
	v_mfma_f32_16x16x32_bf16 v[10:13], v[172:175], v[196:199], v[10:13]
	v_mfma_f32_16x16x32_bf16 v[6:9], v[164:167], v[204:207], v[6:9]
	v_mfma_f32_16x16x32_bf16 v[2:5], v[172:175], v[204:207], v[2:5]
	s_setprio 0
	s_barrier
	s_add_i32 s49, 0, 0x18000
	s_add_i32 s50, 0, 0x1c000
	v_add_u32_e32 v156, s49, v141
	v_add_u32_e32 v172, s50, v141
	ds_read_b128 v[144:147], v156
	ds_read_b128 v[148:151], v156 offset:1024
	ds_read_b128 v[152:155], v156 offset:2048
	ds_read_b128 v[156:159], v156 offset:3072
	ds_read_b128 v[160:163], v172
	ds_read_b128 v[164:167], v172 offset:1024
	ds_read_b128 v[168:171], v172 offset:2048
	ds_read_b128 v[172:175], v172 offset:3072
	s_add_u32 s26, s26, 0x40000
	s_addc_u32 s27, s27, 0
	s_mov_b32 m0, s39
	ds_read_b128 v[176:179], v143 offset:32768
	ds_read_b128 v[180:183], v143 offset:33792
	ds_read_b128 v[184:187], v143 offset:34816
	ds_read_b128 v[188:191], v143 offset:35840
	ds_read_b128 v[192:195], v143 offset:36864
	ds_read_b128 v[196:199], v143 offset:37888
	ds_read_b128 v[200:203], v143 offset:38912
	ds_read_b128 v[204:207], v143 offset:39936
	global_load_lds_dwordx4 v134, s[26:27]
	s_mov_b32 m0, s40
	s_nop 0
	global_load_lds_dwordx4 v132, s[26:27]
	s_waitcnt vmcnt(8)
	s_waitcnt lgkmcnt(0)
	s_barrier
	s_setprio 1
	s_waitcnt lgkmcnt(0)
	v_mfma_f32_16x16x32_bf16 v[126:129], v[144:147], v[176:179], v[126:129]
	v_mfma_f32_16x16x32_bf16 v[122:125], v[152:155], v[176:179], v[122:125]
	v_mfma_f32_16x16x32_bf16 v[118:121], v[144:147], v[184:187], v[118:121]
	v_mfma_f32_16x16x32_bf16 v[114:117], v[152:155], v[184:187], v[114:117]
	v_mfma_f32_16x16x32_bf16 v[102:105], v[144:147], v[192:195], v[102:105]
	v_mfma_f32_16x16x32_bf16 v[98:101], v[152:155], v[192:195], v[98:101]
	v_mfma_f32_16x16x32_bf16 v[86:89], v[144:147], v[200:203], v[86:89]
	v_mfma_f32_16x16x32_bf16 v[82:85], v[152:155], v[200:203], v[82:85]
	v_mfma_f32_16x16x32_bf16 v[126:129], v[148:151], v[180:183], v[126:129]
	v_mfma_f32_16x16x32_bf16 v[122:125], v[156:159], v[180:183], v[122:125]
	v_mfma_f32_16x16x32_bf16 v[118:121], v[148:151], v[188:191], v[118:121]
	v_mfma_f32_16x16x32_bf16 v[114:117], v[156:159], v[188:191], v[114:117]
	v_mfma_f32_16x16x32_bf16 v[102:105], v[148:151], v[196:199], v[102:105]
	v_mfma_f32_16x16x32_bf16 v[98:101], v[156:159], v[196:199], v[98:101]
	v_mfma_f32_16x16x32_bf16 v[86:89], v[148:151], v[204:207], v[86:89]
	v_mfma_f32_16x16x32_bf16 v[82:85], v[156:159], v[204:207], v[82:85]
	s_setprio 0
	s_setprio 1
	v_mfma_f32_16x16x32_bf16 v[110:113], v[160:163], v[176:179], v[110:113]
	v_mfma_f32_16x16x32_bf16 v[106:109], v[168:171], v[176:179], v[106:109]
	v_mfma_f32_16x16x32_bf16 v[94:97], v[160:163], v[184:187], v[94:97]
	v_mfma_f32_16x16x32_bf16 v[90:93], v[168:171], v[184:187], v[90:93]
	v_mfma_f32_16x16x32_bf16 v[78:81], v[160:163], v[192:195], v[78:81]
	v_mfma_f32_16x16x32_bf16 v[74:77], v[168:171], v[192:195], v[74:77]
	v_mfma_f32_16x16x32_bf16 v[70:73], v[160:163], v[200:203], v[70:73]
	v_mfma_f32_16x16x32_bf16 v[66:69], v[168:171], v[200:203], v[66:69]
	v_mfma_f32_16x16x32_bf16 v[110:113], v[164:167], v[180:183], v[110:113]
	v_mfma_f32_16x16x32_bf16 v[106:109], v[172:175], v[180:183], v[106:109]
	v_mfma_f32_16x16x32_bf16 v[94:97], v[164:167], v[188:191], v[94:97]
	v_mfma_f32_16x16x32_bf16 v[90:93], v[172:175], v[188:191], v[90:93]
	v_mfma_f32_16x16x32_bf16 v[78:81], v[164:167], v[196:199], v[78:81]
	v_mfma_f32_16x16x32_bf16 v[74:77], v[172:175], v[196:199], v[74:77]
	v_mfma_f32_16x16x32_bf16 v[70:73], v[164:167], v[204:207], v[70:73]
	v_mfma_f32_16x16x32_bf16 v[66:69], v[172:175], v[204:207], v[66:69]
	s_setprio 0
	s_barrier
; #define PG8_STAGE(bufoff, gbase, voff) do { _Pragma("unroll") for (int _i = 0; _i < 2; ++_i) \
;         __builtin_amdgcn_global_load_lds((const unsigned*)((const char*)(gbase) + (voff)[_i]), (PG8_LAS unsigned*)(lds + (bufoff) + ldsw + _i * 8192), 16, 0, 0); } while (0)
; #define PG8_WAIT_V(n) asm volatile("s_waitcnt vmcnt(" #n ")" ::: "memory")
; #define PG8_WAIT_L(n) asm volatile("s_waitcnt lgkmcnt(" #n ")" ::: "memory")
; #define PG8_BAR __builtin_amdgcn_s_barrier()
; #define PG8_SCHED __builtin_amdgcn_sched_barrier(0)
; #define PG8_STAGEA(bufoff, gbase, h, vsel) do { if constexpr (GATHER) { PG8_STAGE(bufoff, gbase, vsel[h]); } else { PG8_STAGE(bufoff, (gbase) + (h) * hstep, voffA); } } while (0)
; template <class Epi, class Sched, bool ALIGN_EPI = false, bool SP2 = false, bool F8 = false, bool GATHER = false>
; __device__ __forceinline__ void gemm_phase(PG8_LAS unsigned char* lds, const Gemm g, const Sched& S, const Epi& E, const int tid_in) {
;     ...
;         for (int t = 0; t < nt; t += 2) {
;             const bool last = (t == nt - 2);
;             const char* a1 = cA + (size_t)(t + 1) * kstep;
;             const char* a2 = last ? nA : cA + (size_t)(t + 2) * kstep; const char* b2 = last ? nB : cB + (size_t)(t + 2) * kstep;
;             const char* a3 = a2 + kstep; const char* b3 = b2 + kstep;
;     ...
;             PG8_LDA(At, 1, 1); PG8_STAGE(PG8_SB(1, 0), b3, voffB); PG8_STAGE(PG8_SB(1, 1), b3 + hstep, voffB); PG8_STAGEA(PG8_SA(1, 0), a3, 0, vS);
;             PG8_WAIT_V(8); PG8_WAIT_L(0); PG8_BAR; PG8_MMA(1, 0, At, B0); PG8_MMA(1, 1, At, B1); PG8_BAR; PG8_SCHED;
	s_add_i32 s26, s49, s35
	v_lshl_add_u64 v[208:209], v[208:209], 0, s[0:1]
	s_mov_b32 m0, s26
	ds_read_b128 v[176:179], v143 offset:49152
	ds_read_b128 v[180:183], v143 offset:50176
	ds_read_b128 v[184:187], v143 offset:51200
	ds_read_b128 v[188:191], v143 offset:52224
	ds_read_b128 v[192:195], v143 offset:53248
	ds_read_b128 v[196:199], v143 offset:54272
	ds_read_b128 v[200:203], v143 offset:55296
	ds_read_b128 v[204:207], v143 offset:56320
	global_load_lds_dwordx4 v[208:209], off
	s_add_i32 m0, s26, 0x2000
	s_add_u32 s24, s24, 0x40080
	v_lshl_add_u64 v[208:209], v[210:211], 0, s[0:1]
	s_addc_u32 s25, s25, 0
	s_add_i32 s26, s50, s35
	global_load_lds_dwordx4 v[208:209], off
	s_mov_b32 m0, s26
	s_nop 0
	global_load_lds_dwordx4 v0, s[24:25]
	s_add_i32 m0, s26, 0x2000
	s_nop 0
	global_load_lds_dwordx4 v130, s[24:25]
	v_lshl_add_u64 v[208:209], v[212:213], 0, s[0:1]
	s_mov_b32 m0, s41
	s_nop 0
	global_load_lds_dwordx4 v[208:209], off
	v_lshl_add_u64 v[208:209], v[214:215], 0, s[0:1]
	s_mov_b32 m0, s42
	s_nop 0
	global_load_lds_dwordx4 v[208:209], off
	s_waitcnt vmcnt(8)
	s_waitcnt lgkmcnt(0)
	s_barrier
	s_setprio 1
	s_waitcnt lgkmcnt(0)
	v_mfma_f32_16x16x32_bf16 v[62:65], v[144:147], v[176:179], v[62:65]
	v_mfma_f32_16x16x32_bf16 v[58:61], v[152:155], v[176:179], v[58:61]
	v_mfma_f32_16x16x32_bf16 v[54:57], v[144:147], v[184:187], v[54:57]
	v_mfma_f32_16x16x32_bf16 v[50:53], v[152:155], v[184:187], v[50:53]
	v_mfma_f32_16x16x32_bf16 v[38:41], v[144:147], v[192:195], v[38:41]
	v_mfma_f32_16x16x32_bf16 v[34:37], v[152:155], v[192:195], v[34:37]
	v_mfma_f32_16x16x32_bf16 v[22:25], v[144:147], v[200:203], v[22:25]
	v_mfma_f32_16x16x32_bf16 v[18:21], v[152:155], v[200:203], v[18:21]
	v_mfma_f32_16x16x32_bf16 v[62:65], v[148:151], v[180:183], v[62:65]
	v_mfma_f32_16x16x32_bf16 v[58:61], v[156:159], v[180:183], v[58:61]
	v_mfma_f32_16x16x32_bf16 v[54:57], v[148:151], v[188:191], v[54:57]
	v_mfma_f32_16x16x32_bf16 v[50:53], v[156:159], v[188:191], v[50:53]
	v_mfma_f32_16x16x32_bf16 v[38:41], v[148:151], v[196:199], v[38:41]
	v_mfma_f32_16x16x32_bf16 v[34:37], v[156:159], v[196:199], v[34:37]
	v_mfma_f32_16x16x32_bf16 v[22:25], v[148:151], v[204:207], v[22:25]
	v_mfma_f32_16x16x32_bf16 v[18:21], v[156:159], v[204:207], v[18:21]
	s_setprio 0
	s_setprio 1
	v_mfma_f32_16x16x32_bf16 v[46:49], v[160:163], v[176:179], v[46:49]
	v_mfma_f32_16x16x32_bf16 v[42:45], v[168:171], v[176:179], v[42:45]
	v_mfma_f32_16x16x32_bf16 v[30:33], v[160:163], v[184:187], v[30:33]
	v_mfma_f32_16x16x32_bf16 v[26:29], v[168:171], v[184:187], v[26:29]
	v_mfma_f32_16x16x32_bf16 v[14:17], v[160:163], v[192:195], v[14:17]
	v_mfma_f32_16x16x32_bf16 v[10:13], v[168:171], v[192:195], v[10:13]
	v_mfma_f32_16x16x32_bf16 v[6:9], v[160:163], v[200:203], v[6:9]
	v_mfma_f32_16x16x32_bf16 v[2:5], v[168:171], v[200:203], v[2:5]
	v_mfma_f32_16x16x32_bf16 v[46:49], v[164:167], v[180:183], v[46:49]
	v_mfma_f32_16x16x32_bf16 v[42:45], v[172:175], v[180:183], v[42:45]
	v_mfma_f32_16x16x32_bf16 v[30:33], v[164:167], v[188:191], v[30:33]
	v_mfma_f32_16x16x32_bf16 v[26:29], v[172:175], v[188:191], v[26:29]
	v_mfma_f32_16x16x32_bf16 v[14:17], v[164:167], v[196:199], v[14:17]
	v_mfma_f32_16x16x32_bf16 v[10:13], v[172:175], v[196:199], v[10:13]
	v_mfma_f32_16x16x32_bf16 v[6:9], v[164:167], v[204:207], v[6:9]
	v_mfma_f32_16x16x32_bf16 v[2:5], v[172:175], v[204:207], v[2:5]
	s_setprio 0
	s_barrier
	s_add_i32 s48, s48, 2
	s_add_u32 s22, s22, 0x100
	s_addc_u32 s23, s23, 0
	s_add_u32 s46, s46, 0x100
	s_addc_u32 s47, s47, 0
	s_cmp_gt_u32 s48, 13
	s_cbranch_scc0 .LBB0_1324
	s_and_b64 vcc, exec, s[8:9]
	s_cbranch_vccz .LBB0_1327
	s_barrier

; #define PG8_STAGE(bufoff, gbase, voff) do { _Pragma("unroll") for (int _i = 0; _i < 2; ++_i) \
;         __builtin_amdgcn_global_load_lds((const unsigned*)((const char*)(gbase) + (voff)[_i]), (PG8_LAS unsigned*)(lds + (bufoff) + ldsw + _i * 8192), 16, 0, 0); } while (0)
; #define PG8_WAIT_V(n) asm volatile("s_waitcnt vmcnt(" #n ")" ::: "memory")
; #define PG8_WAIT_L(n) asm volatile("s_waitcnt lgkmcnt(" #n ")" ::: "memory")
; #define PG8_BAR __builtin_amdgcn_s_barrier()
; #define PG8_SCHED __builtin_amdgcn_sched_barrier(0)
; #define PG8_STAGEA(bufoff, gbase, h, vsel) do { if constexpr (GATHER) { PG8_STAGE(bufoff, gbase, vsel[h]); } else { PG8_STAGE(bufoff, (gbase) + (h) * hstep, voffA); } } while (0)
; template <class Epi, class Sched, bool ALIGN_EPI = false, bool SP2 = false, bool F8 = false, bool GATHER = false>
; __device__ __forceinline__ void gemm_phase(PG8_LAS unsigned char* lds, const Gemm g, const Sched& S, const Epi& E, const int tid_in) {
;     ...
;                 for (int h = 0; h < 2; ++h)
; #pragma unroll
;                     for (int i = 0; i < 2; ++i) vS[h][i] = (last && has_next) ? vN[h][i] : vC[h][i];
;             }
;             if constexpr (SP2) {
;             PG8_LDB(B0, 0, 0); PG8_LDB(B1, 0, 1); PG8_SCHED; PG8_LDA(At, 0, 0); PG8_STAGEA(PG8_SA(1, 1), a1, 1, vC);
;             PG8_WAIT_V(8); PG8_WAIT_L(0); PG8_BAR; PG8_MMA(0, 0, At, B0); PG8_MMA(0, 1, At, B1); PG8_BAR; PG8_SCHED;
;             PG8_LDA(At, 0, 1); PG8_STAGE(PG8_SB(0, 0), b2, voffB); PG8_STAGE(PG8_SB(0, 1), b2 + hstep, voffB); PG8_STAGEA(PG8_SA(0, 0), a2, 0, vS);
.LBB0_2174:
	s_add_u32 s34, s2, s28
	s_addc_u32 s35, s3, s29
	s_add_u32 s63, s34, 0x23a40100
	s_addc_u32 s64, s35, 0
	s_and_b64 s[34:35], s[30:31], exec
	s_cselect_b32 s35, s13, s64
	s_cselect_b32 s34, s12, s63
	s_add_u32 s63, s25, s28
	s_addc_u32 s64, s57, s29
	s_and_b64 s[30:31], s[30:31], exec
	s_cselect_b32 s31, s60, s64
	s_cselect_b32 s30, s61, s63
	s_add_i32 s63, 0, 0x10000
	v_add_u32_e32 v151, s63, v164
	s_add_i32 s66, 0, 0x14000
	ds_read_b128 v[170:173], v151
	ds_read_b128 v[174:177], v151 offset:1024
	ds_read_b128 v[178:181], v151 offset:2048
	ds_read_b128 v[182:185], v151 offset:3072
	v_add_u32_e32 v151, s66, v164
	ds_read_b128 v[186:189], v151
	ds_read_b128 v[190:193], v151 offset:1024
	ds_read_b128 v[194:197], v151 offset:2048
	ds_read_b128 v[198:201], v151 offset:3072
	v_lshl_add_u64 v[152:153], v[144:145], 0, s[28:29]
	s_add_i32 m0, s45, 0xc000
	ds_read_b128 v[202:205], v165
	ds_read_b128 v[206:209], v165 offset:1024
	ds_read_b128 v[210:213], v165 offset:2048
	ds_read_b128 v[214:217], v165 offset:3072
	ds_read_b128 v[218:221], v165 offset:4096
	ds_read_b128 v[222:225], v165 offset:5120
	ds_read_b128 v[226:229], v165 offset:6144
	ds_read_b128 v[230:233], v165 offset:7168
	global_load_lds_dwordx4 v[152:153], off
	v_lshl_add_u64 v[152:153], v[142:143], 0, s[28:29]
	s_add_i32 m0, s45, 0xe000
	s_nop 0
	global_load_lds_dwordx4 v[152:153], off
	s_waitcnt vmcnt(8)
	s_waitcnt lgkmcnt(0)
	s_barrier
	s_setprio 1
	s_waitcnt lgkmcnt(0)
	v_mfma_scale_f32_16x16x128_f8f6f4 v[110:113], v[170:177], v[202:209], v[110:113], v235, v235 op_sel_hi:[0,0,0]
	v_mfma_scale_f32_16x16x128_f8f6f4 v[106:109], v[178:185], v[202:209], v[106:109], v235, v235 op_sel_hi:[0,0,0]
	v_mfma_scale_f32_16x16x128_f8f6f4 v[102:105], v[170:177], v[210:217], v[102:105], v235, v235 op_sel_hi:[0,0,0]
	v_mfma_scale_f32_16x16x128_f8f6f4 v[98:101], v[178:185], v[210:217], v[98:101], v235, v235 op_sel_hi:[0,0,0]
	v_mfma_scale_f32_16x16x128_f8f6f4 v[94:97], v[170:177], v[218:225], v[94:97], v235, v235 op_sel_hi:[0,0,0]
	v_mfma_scale_f32_16x16x128_f8f6f4 v[90:93], v[178:185], v[218:225], v[90:93], v235, v235 op_sel_hi:[0,0,0]
	v_mfma_scale_f32_16x16x128_f8f6f4 v[86:89], v[170:177], v[226:233], v[86:89], v235, v235 op_sel_hi:[0,0,0]
	v_mfma_scale_f32_16x16x128_f8f6f4 v[82:85], v[178:185], v[226:233], v[82:85], v235, v235 op_sel_hi:[0,0,0]
	s_setprio 0
	s_setprio 1
	v_mfma_scale_f32_16x16x128_f8f6f4 v[78:81], v[186:193], v[202:209], v[78:81], v235, v235 op_sel_hi:[0,0,0]
	v_mfma_scale_f32_16x16x128_f8f6f4 v[74:77], v[194:201], v[202:209], v[74:77], v235, v235 op_sel_hi:[0,0,0]
	v_mfma_scale_f32_16x16x128_f8f6f4 v[70:73], v[186:193], v[210:217], v[70:73], v235, v235 op_sel_hi:[0,0,0]
	v_mfma_scale_f32_16x16x128_f8f6f4 v[66:69], v[194:201], v[210:217], v[66:69], v235, v235 op_sel_hi:[0,0,0]
	v_mfma_scale_f32_16x16x128_f8f6f4 v[62:65], v[186:193], v[218:225], v[62:65], v235, v235 op_sel_hi:[0,0,0]
	v_mfma_scale_f32_16x16x128_f8f6f4 v[58:61], v[194:201], v[218:225], v[58:61], v235, v235 op_sel_hi:[0,0,0]
	v_mfma_scale_f32_16x16x128_f8f6f4 v[54:57], v[186:193], v[226:233], v[54:57], v235, v235 op_sel_hi:[0,0,0]
	v_mfma_scale_f32_16x16x128_f8f6f4 v[50:53], v[194:201], v[226:233], v[50:53], v235, v235 op_sel_hi:[0,0,0]
	s_setprio 0
	s_barrier
	s_add_i32 s63, s63, s39
	v_lshl_add_u64 v[152:153], s[30:31], 0, v[132:133]
	s_mov_b32 m0, s63
	ds_read_b128 v[202:205], v165 offset:16384
	ds_read_b128 v[206:209], v165 offset:17408
	ds_read_b128 v[210:213], v165 offset:18432
	ds_read_b128 v[214:217], v165 offset:19456
	ds_read_b128 v[218:221], v165 offset:20480
	ds_read_b128 v[222:225], v165 offset:21504
	ds_read_b128 v[226:229], v165 offset:22528
	ds_read_b128 v[230:233], v165 offset:23552
	global_load_lds_dwordx4 v132, s[30:31]
	s_add_i32 m0, s63, 0x2000
	s_add_u32 s64, s30, 0x20000
	v_lshl_add_u64 v[154:155], s[30:31], 0, v[130:131]
	s_addc_u32 s65, s31, 0
	s_add_i32 s63, s66, s39
	global_load_lds_dwordx4 v130, s[30:31]
	s_mov_b32 m0, s63
	v_mov_b32_e32 v151, v1
	global_load_lds_dwordx4 v132, s[64:65]
	s_add_i32 m0, s63, 0x2000
	s_nop 0
	global_load_lds_dwordx4 v130, s[64:65]
	s_mov_b32 m0, s45
	v_lshl_add_u64 v[156:157], s[34:35], 0, v[0:1]
	global_load_lds_dwordx4 v0, s[34:35]
	s_mov_b32 m0, s46
	s_nop 0
	global_load_lds_dwordx4 v150, s[34:35]
	s_waitcnt vmcnt(8)
	s_waitcnt lgkmcnt(0)
	v_lshl_add_u64 v[150:151], s[34:35], 0, v[150:151]
	s_barrier
	s_setprio 1
	s_waitcnt lgkmcnt(0)
	v_mfma_scale_f32_16x16x128_f8f6f4 v[46:49], v[170:177], v[202:209], v[46:49], v235, v235 op_sel_hi:[0,0,0]
	v_mfma_scale_f32_16x16x128_f8f6f4 v[42:45], v[178:185], v[202:209], v[42:45], v235, v235 op_sel_hi:[0,0,0]
	v_mfma_scale_f32_16x16x128_f8f6f4 v[38:41], v[170:177], v[210:217], v[38:41], v235, v235 op_sel_hi:[0,0,0]
	v_mfma_scale_f32_16x16x128_f8f6f4 v[34:37], v[178:185], v[210:217], v[34:37], v235, v235 op_sel_hi:[0,0,0]
	v_mfma_scale_f32_16x16x128_f8f6f4 v[30:33], v[170:177], v[218:225], v[30:33], v235, v235 op_sel_hi:[0,0,0]
	v_mfma_scale_f32_16x16x128_f8f6f4 v[26:29], v[178:185], v[218:225], v[26:29], v235, v235 op_sel_hi:[0,0,0]
	v_mfma_scale_f32_16x16x128_f8f6f4 v[22:25], v[170:177], v[226:233], v[22:25], v235, v235 op_sel_hi:[0,0,0]
	v_mfma_scale_f32_16x16x128_f8f6f4 v[18:21], v[178:185], v[226:233], v[18:21], v235, v235 op_sel_hi:[0,0,0]
	s_setprio 0
	s_setprio 1
	v_mfma_scale_f32_16x16x128_f8f6f4 v[14:17], v[186:193], v[202:209], v[14:17], v235, v235 op_sel_hi:[0,0,0]
	v_mfma_scale_f32_16x16x128_f8f6f4 v[10:13], v[194:201], v[202:209], v[10:13], v235, v235 op_sel_hi:[0,0,0]
	v_mfma_scale_f32_16x16x128_f8f6f4 v[6:9], v[186:193], v[210:217], v[6:9], v235, v235 op_sel_hi:[0,0,0]
	v_mfma_scale_f32_16x16x128_f8f6f4 v[2:5], v[194:201], v[210:217], v[2:5], v235, v235 op_sel_hi:[0,0,0]
	v_mfma_scale_f32_16x16x128_f8f6f4 v[114:117], v[186:193], v[218:225], v[114:117], v235, v235 op_sel_hi:[0,0,0]
	v_mfma_scale_f32_16x16x128_f8f6f4 v[118:121], v[194:201], v[218:225], v[118:121], v235, v235 op_sel_hi:[0,0,0]
	v_mfma_scale_f32_16x16x128_f8f6f4 v[122:125], v[186:193], v[226:233], v[122:125], v235, v235 op_sel_hi:[0,0,0]
	v_mfma_scale_f32_16x16x128_f8f6f4 v[126:129], v[194:201], v[226:233], v[126:129], v235, v235 op_sel_hi:[0,0,0]
	s_setprio 0
	s_barrier
; #define PG8_STAGE(bufoff, gbase, voff) do { _Pragma("unroll") for (int _i = 0; _i < 2; ++_i) \
;         __builtin_amdgcn_global_load_lds((const unsigned*)((const char*)(gbase) + (voff)[_i]), (PG8_LAS unsigned*)(lds + (bufoff) + ldsw + _i * 8192), 16, 0, 0); } while (0)
; #define PG8_WAIT_V(n) asm volatile("s_waitcnt vmcnt(" #n ")" ::: "memory")
; #define PG8_WAIT_L(n) asm volatile("s_waitcnt lgkmcnt(" #n ")" ::: "memory")
; #define PG8_BAR __builtin_amdgcn_s_barrier()
; #define PG8_SCHED __builtin_amdgcn_sched_barrier(0)
; #define PG8_STAGEA(bufoff, gbase, h, vsel) do { if constexpr (GATHER) { PG8_STAGE(bufoff, gbase, vsel[h]); } else { PG8_STAGE(bufoff, (gbase) + (h) * hstep, voffA); } } while (0)
; template <class Epi, class Sched, bool ALIGN_EPI = false, bool SP2 = false, bool F8 = false, bool GATHER = false>
; __device__ __forceinline__ void gemm_phase(PG8_LAS unsigned char* lds, const Gemm g, const Sched& S, const Epi& E, const int tid_in) {
;     ...
;             PG8_LDB(B0, 1, 0); PG8_LDB(B1, 1, 1); PG8_SCHED; PG8_LDA(At, 1, 0); PG8_STAGEA(PG8_SA(0, 1), a2, 1, vS);
;             PG8_WAIT_V(8); PG8_WAIT_L(0); PG8_BAR; PG8_MMA(0, 0, At, B0); PG8_MMA(0, 1, At, B1); PG8_BAR; PG8_SCHED;
;             PG8_LDA(At, 1, 1); PG8_STAGE(PG8_SB(1, 0), b3, voffB); PG8_STAGE(PG8_SB(1, 1), b3 + hstep, voffB); PG8_STAGEA(PG8_SA(1, 0), a3, 0, vS);
;             PG8_WAIT_V(8); PG8_WAIT_L(0); PG8_BAR; PG8_MMA(1, 0, At, B0); PG8_MMA(1, 1, At, B1); PG8_BAR; PG8_SCHED;
	s_add_i32 s63, 0, 0x18000
	v_add_u32_e32 v0, s63, v164
	s_add_i32 s64, 0, 0x1c000
	ds_read_b128 v[170:173], v0
	ds_read_b128 v[174:177], v0 offset:1024
	ds_read_b128 v[178:181], v0 offset:2048
	ds_read_b128 v[182:185], v0 offset:3072
	v_add_u32_e32 v0, s64, v164
	ds_read_b128 v[186:189], v0
	ds_read_b128 v[190:193], v0 offset:1024
	ds_read_b128 v[194:197], v0 offset:2048
	ds_read_b128 v[198:201], v0 offset:3072
	s_mov_b32 m0, s47
	v_lshl_add_u64 v[148:149], s[34:35], 0, v[148:149]
	ds_read_b128 v[202:205], v165 offset:32768
	ds_read_b128 v[206:209], v165 offset:33792
	ds_read_b128 v[210:213], v165 offset:34816
	ds_read_b128 v[214:217], v165 offset:35840
	ds_read_b128 v[218:221], v165 offset:36864
	ds_read_b128 v[222:225], v165 offset:37888
	ds_read_b128 v[226:229], v165 offset:38912
	ds_read_b128 v[230:233], v165 offset:39936
	global_load_lds_dwordx4 v[148:149], off
	v_lshl_add_u64 v[146:147], s[34:35], 0, v[146:147]
	s_mov_b32 m0, s48
	s_nop 0
	global_load_lds_dwordx4 v[146:147], off
	s_waitcnt vmcnt(8)
	s_waitcnt lgkmcnt(0)
	s_barrier
	s_setprio 1
	s_waitcnt lgkmcnt(0)
	v_mfma_scale_f32_16x16x128_f8f6f4 v[110:113], v[170:177], v[202:209], v[110:113], v235, v235 op_sel_hi:[0,0,0]
	v_mfma_scale_f32_16x16x128_f8f6f4 v[106:109], v[178:185], v[202:209], v[106:109], v235, v235 op_sel_hi:[0,0,0]
	v_mfma_scale_f32_16x16x128_f8f6f4 v[102:105], v[170:177], v[210:217], v[102:105], v235, v235 op_sel_hi:[0,0,0]
	v_mfma_scale_f32_16x16x128_f8f6f4 v[98:101], v[178:185], v[210:217], v[98:101], v235, v235 op_sel_hi:[0,0,0]
	v_mfma_scale_f32_16x16x128_f8f6f4 v[94:97], v[170:177], v[218:225], v[94:97], v235, v235 op_sel_hi:[0,0,0]
	v_mfma_scale_f32_16x16x128_f8f6f4 v[90:93], v[178:185], v[218:225], v[90:93], v235, v235 op_sel_hi:[0,0,0]
	v_mfma_scale_f32_16x16x128_f8f6f4 v[86:89], v[170:177], v[226:233], v[86:89], v235, v235 op_sel_hi:[0,0,0]
	v_mfma_scale_f32_16x16x128_f8f6f4 v[82:85], v[178:185], v[226:233], v[82:85], v235, v235 op_sel_hi:[0,0,0]
	s_setprio 0
	s_setprio 1
	v_mfma_scale_f32_16x16x128_f8f6f4 v[78:81], v[186:193], v[202:209], v[78:81], v235, v235 op_sel_hi:[0,0,0]
	v_mfma_scale_f32_16x16x128_f8f6f4 v[74:77], v[194:201], v[202:209], v[74:77], v235, v235 op_sel_hi:[0,0,0]
	v_mfma_scale_f32_16x16x128_f8f6f4 v[70:73], v[186:193], v[210:217], v[70:73], v235, v235 op_sel_hi:[0,0,0]
	v_mfma_scale_f32_16x16x128_f8f6f4 v[66:69], v[194:201], v[210:217], v[66:69], v235, v235 op_sel_hi:[0,0,0]
	v_mfma_scale_f32_16x16x128_f8f6f4 v[62:65], v[186:193], v[218:225], v[62:65], v235, v235 op_sel_hi:[0,0,0]
	v_mfma_scale_f32_16x16x128_f8f6f4 v[58:61], v[194:201], v[218:225], v[58:61], v235, v235 op_sel_hi:[0,0,0]
	v_mfma_scale_f32_16x16x128_f8f6f4 v[54:57], v[186:193], v[226:233], v[54:57], v235, v235 op_sel_hi:[0,0,0]
	v_mfma_scale_f32_16x16x128_f8f6f4 v[50:53], v[194:201], v[226:233], v[50:53], v235, v235 op_sel_hi:[0,0,0]
	s_setprio 0
	s_barrier
	s_add_i32 s34, s63, s39
	v_lshl_add_u64 v[146:147], v[152:153], 0, s[0:1]
	s_mov_b32 m0, s34
	ds_read_b128 v[202:205], v165 offset:49152
	ds_read_b128 v[206:209], v165 offset:50176
	ds_read_b128 v[210:213], v165 offset:51200
	ds_read_b128 v[214:217], v165 offset:52224
	ds_read_b128 v[218:221], v165 offset:53248
	ds_read_b128 v[222:225], v165 offset:54272
	ds_read_b128 v[226:229], v165 offset:55296
	ds_read_b128 v[230:233], v165 offset:56320
	global_load_lds_dwordx4 v[146:147], off
	s_add_i32 m0, s34, 0x2000
	s_add_u32 s30, s30, 0x20080
	v_lshl_add_u64 v[146:147], v[154:155], 0, s[0:1]
	s_addc_u32 s31, s31, 0
	s_add_i32 s34, s64, s39
	global_load_lds_dwordx4 v[146:147], off
	s_mov_b32 m0, s34
	s_nop 0
	global_load_lds_dwordx4 v132, s[30:31]
	s_add_i32 m0, s34, 0x2000
	s_nop 0
	global_load_lds_dwordx4 v130, s[30:31]
	v_lshl_add_u64 v[146:147], v[156:157], 0, s[0:1]
	s_mov_b32 m0, s49
	s_nop 0
	global_load_lds_dwordx4 v[146:147], off
	v_lshl_add_u64 v[146:147], v[150:151], 0, s[0:1]
	s_mov_b32 m0, s50
	s_nop 0
	global_load_lds_dwordx4 v[146:147], off
	s_waitcnt vmcnt(8)
	s_waitcnt lgkmcnt(0)
	s_barrier
	s_setprio 1
	s_waitcnt lgkmcnt(0)
	v_mfma_scale_f32_16x16x128_f8f6f4 v[46:49], v[170:177], v[202:209], v[46:49], v235, v235 op_sel_hi:[0,0,0]
	v_mfma_scale_f32_16x16x128_f8f6f4 v[42:45], v[178:185], v[202:209], v[42:45], v235, v235 op_sel_hi:[0,0,0]
	v_mfma_scale_f32_16x16x128_f8f6f4 v[38:41], v[170:177], v[210:217], v[38:41], v235, v235 op_sel_hi:[0,0,0]
	v_mfma_scale_f32_16x16x128_f8f6f4 v[34:37], v[178:185], v[210:217], v[34:37], v235, v235 op_sel_hi:[0,0,0]
	v_mfma_scale_f32_16x16x128_f8f6f4 v[30:33], v[170:177], v[218:225], v[30:33], v235, v235 op_sel_hi:[0,0,0]
	v_mfma_scale_f32_16x16x128_f8f6f4 v[26:29], v[178:185], v[218:225], v[26:29], v235, v235 op_sel_hi:[0,0,0]
	v_mfma_scale_f32_16x16x128_f8f6f4 v[22:25], v[170:177], v[226:233], v[22:25], v235, v235 op_sel_hi:[0,0,0]
	v_mfma_scale_f32_16x16x128_f8f6f4 v[18:21], v[178:185], v[226:233], v[18:21], v235, v235 op_sel_hi:[0,0,0]
	s_setprio 0
	s_setprio 1
	v_mfma_scale_f32_16x16x128_f8f6f4 v[14:17], v[186:193], v[202:209], v[14:17], v235, v235 op_sel_hi:[0,0,0]
	v_mfma_scale_f32_16x16x128_f8f6f4 v[10:13], v[194:201], v[202:209], v[10:13], v235, v235 op_sel_hi:[0,0,0]
	v_mfma_scale_f32_16x16x128_f8f6f4 v[6:9], v[186:193], v[210:217], v[6:9], v235, v235 op_sel_hi:[0,0,0]
	v_mfma_scale_f32_16x16x128_f8f6f4 v[2:5], v[194:201], v[210:217], v[2:5], v235, v235 op_sel_hi:[0,0,0]
	v_mfma_scale_f32_16x16x128_f8f6f4 v[114:117], v[186:193], v[218:225], v[114:117], v235, v235 op_sel_hi:[0,0,0]
	v_mfma_scale_f32_16x16x128_f8f6f4 v[118:121], v[194:201], v[218:225], v[118:121], v235, v235 op_sel_hi:[0,0,0]
	v_mfma_scale_f32_16x16x128_f8f6f4 v[122:125], v[186:193], v[226:233], v[122:125], v235, v235 op_sel_hi:[0,0,0]
	v_mfma_scale_f32_16x16x128_f8f6f4 v[126:129], v[194:201], v[226:233], v[126:129], v235, v235 op_sel_hi:[0,0,0]
	s_setprio 0
	s_barrier
	s_add_i32 s62, s62, 2
	s_add_u32 s28, s28, 0x100
	s_addc_u32 s29, s29, 0
	s_cmp_gt_u32 s62, 5
	s_cbranch_scc1 .LBB0_2177

; #define PG8_STAGE(bufoff, gbase, voff) do { _Pragma("unroll") for (int _i = 0; _i < 2; ++_i) \
;         __builtin_amdgcn_global_load_lds((const unsigned*)((const char*)(gbase) + (voff)[_i]), (PG8_LAS unsigned*)(lds + (bufoff) + ldsw + _i * 8192), 16, 0, 0); } while (0)
; #define PG8_WAIT_V(n) asm volatile("s_waitcnt vmcnt(" #n ")" ::: "memory")
; #define PG8_WAIT_L(n) asm volatile("s_waitcnt lgkmcnt(" #n ")" ::: "memory")
; #define PG8_BAR __builtin_amdgcn_s_barrier()
; #define PG8_SCHED __builtin_amdgcn_sched_barrier(0)
; #define PG8_STAGEA(bufoff, gbase, h, vsel) do { if constexpr (GATHER) { PG8_STAGE(bufoff, gbase, vsel[h]); } else { PG8_STAGE(bufoff, (gbase) + (h) * hstep, voffA); } } while (0)
; template <class Epi, class Sched, bool ALIGN_EPI = false, bool SP2 = false, bool F8 = false, bool GATHER = false>
; __device__ __forceinline__ void gemm_phase(PG8_LAS unsigned char* lds, const Gemm g, const Sched& S, const Epi& E, const int tid_in) {
;     ...
;             PG8_LDB(B0, 0, 0); PG8_LDB(B1, 0, 1); PG8_SCHED; PG8_LDA(At, 0, 0); PG8_STAGEA(PG8_SA(1, 1), a1, 1, vC);
;             PG8_WAIT_V(8); PG8_WAIT_L(0); PG8_BAR; PG8_MMA(0, 0, At, B0); PG8_MMA(0, 1, At, B1); PG8_BAR; PG8_SCHED;
;             PG8_LDA(At, 0, 1); PG8_STAGE(PG8_SB(0, 0), b2, voffB); PG8_STAGE(PG8_SB(0, 1), b2 + hstep, voffB); PG8_STAGEA(PG8_SA(0, 0), a2, 0, vS);
.LBB0_2249:
	s_add_u32 s18, s16, 0x100
	s_addc_u32 s19, s17, 0
	s_add_i32 s50, 0, 0x10000
	s_cmp_eq_u32 s49, 18
	s_cselect_b32 s23, s7, s19
	s_cselect_b32 s22, s6, s18
	v_add_u32_e32 v140, s50, v149
	s_cselect_b32 s21, s15, s48
	s_cselect_b32 s20, s14, s47
	s_add_i32 s51, 0, 0x14000
	ds_read_b128 v[152:155], v140
	ds_read_b128 v[156:159], v140 offset:1024
	ds_read_b128 v[160:163], v140 offset:2048
	ds_read_b128 v[164:167], v140 offset:3072
	v_add_u32_e32 v140, s51, v149
	ds_read_b128 v[168:171], v140
	ds_read_b128 v[172:175], v140 offset:1024
	ds_read_b128 v[176:179], v140 offset:2048
	ds_read_b128 v[180:183], v140 offset:3072
	v_lshl_add_u64 v[208:209], s[16:17], 0, v[136:137]
	s_add_i32 m0, s33, 0xc000
	ds_read_b128 v[140:143], v151
	ds_read_b128 v[144:147], v151 offset:1024
	ds_read_b128 v[184:187], v151 offset:2048
	ds_read_b128 v[188:191], v151 offset:3072
	ds_read_b128 v[192:195], v151 offset:4096
	ds_read_b128 v[196:199], v151 offset:5120
	ds_read_b128 v[200:203], v151 offset:6144
	ds_read_b128 v[204:207], v151 offset:7168
	global_load_lds_dwordx4 v[208:209], off
	v_lshl_add_u64 v[208:209], s[16:17], 0, v[138:139]
	s_add_i32 m0, s33, 0xe000
	s_nop 0
	global_load_lds_dwordx4 v[208:209], off
	s_waitcnt vmcnt(8)
	s_waitcnt lgkmcnt(0)
	s_barrier
	s_setprio 1
	s_waitcnt lgkmcnt(0)
	v_mfma_scale_f32_16x16x128_f8f6f4 v[126:129], v[152:159], v[140:147], v[126:129], v235, v235 op_sel_hi:[0,0,0]
	v_mfma_scale_f32_16x16x128_f8f6f4 v[122:125], v[160:167], v[140:147], v[122:125], v235, v235 op_sel_hi:[0,0,0]
	v_mfma_scale_f32_16x16x128_f8f6f4 v[118:121], v[152:159], v[184:191], v[118:121], v235, v235 op_sel_hi:[0,0,0]
	v_mfma_scale_f32_16x16x128_f8f6f4 v[110:113], v[160:167], v[184:191], v[110:113], v235, v235 op_sel_hi:[0,0,0]
	v_mfma_scale_f32_16x16x128_f8f6f4 v[102:105], v[152:159], v[192:199], v[102:105], v235, v235 op_sel_hi:[0,0,0]
	v_mfma_scale_f32_16x16x128_f8f6f4 v[94:97], v[160:167], v[192:199], v[94:97], v235, v235 op_sel_hi:[0,0,0]
	v_mfma_scale_f32_16x16x128_f8f6f4 v[86:89], v[152:159], v[200:207], v[86:89], v235, v235 op_sel_hi:[0,0,0]
	v_mfma_scale_f32_16x16x128_f8f6f4 v[78:81], v[160:167], v[200:207], v[78:81], v235, v235 op_sel_hi:[0,0,0]
	s_setprio 0
	s_setprio 1
	v_mfma_scale_f32_16x16x128_f8f6f4 v[114:117], v[168:175], v[140:147], v[114:117], v235, v235 op_sel_hi:[0,0,0]
	v_mfma_scale_f32_16x16x128_f8f6f4 v[106:109], v[176:183], v[140:147], v[106:109], v235, v235 op_sel_hi:[0,0,0]
	v_mfma_scale_f32_16x16x128_f8f6f4 v[98:101], v[168:175], v[184:191], v[98:101], v235, v235 op_sel_hi:[0,0,0]
	v_mfma_scale_f32_16x16x128_f8f6f4 v[90:93], v[176:183], v[184:191], v[90:93], v235, v235 op_sel_hi:[0,0,0]
	v_mfma_scale_f32_16x16x128_f8f6f4 v[82:85], v[168:175], v[192:199], v[82:85], v235, v235 op_sel_hi:[0,0,0]
	v_mfma_scale_f32_16x16x128_f8f6f4 v[74:77], v[176:183], v[192:199], v[74:77], v235, v235 op_sel_hi:[0,0,0]
	v_mfma_scale_f32_16x16x128_f8f6f4 v[70:73], v[168:175], v[200:207], v[70:73], v235, v235 op_sel_hi:[0,0,0]
	v_mfma_scale_f32_16x16x128_f8f6f4 v[66:69], v[176:183], v[200:207], v[66:69], v235, v235 op_sel_hi:[0,0,0]
	s_setprio 0
	s_barrier
	s_add_i32 s16, s50, s28
	v_lshl_add_u64 v[140:141], s[20:21], 0, v[0:1]
	s_mov_b32 m0, s16
	ds_read_b128 v[184:187], v151 offset:16384
	ds_read_b128 v[188:191], v151 offset:17408
	ds_read_b128 v[192:195], v151 offset:18432
	ds_read_b128 v[196:199], v151 offset:19456
	ds_read_b128 v[200:203], v151 offset:20480
	ds_read_b128 v[204:207], v151 offset:21504
	ds_read_b128 v[208:211], v151 offset:22528
	ds_read_b128 v[212:215], v151 offset:23552
	global_load_lds_dwordx4 v0, s[20:21]
	s_add_i32 m0, s16, 0x2000
	s_add_u32 s16, s20, 0x58000
	v_lshl_add_u64 v[142:143], s[20:21], 0, v[130:131]
	s_addc_u32 s17, s21, 0
	s_add_i32 s50, s51, s28
	global_load_lds_dwordx4 v130, s[20:21]
	s_mov_b32 m0, s50
	v_lshl_add_u64 v[146:147], s[22:23], 0, v[132:133]
	global_load_lds_dwordx4 v0, s[16:17]
	s_add_i32 m0, s50, 0x2000
	s_nop 0
	global_load_lds_dwordx4 v130, s[16:17]
	v_lshl_add_u64 v[144:145], s[22:23], 0, v[134:135]
	s_mov_b32 m0, s33
	s_nop 0
	global_load_lds_dwordx4 v134, s[22:23]
	s_mov_b32 m0, s34
	s_nop 0
	global_load_lds_dwordx4 v132, s[22:23]
	s_waitcnt vmcnt(8)
	s_waitcnt lgkmcnt(0)
	s_barrier
	s_setprio 1
	s_waitcnt lgkmcnt(0)
	v_mfma_scale_f32_16x16x128_f8f6f4 v[62:65], v[152:159], v[184:191], v[62:65], v235, v235 op_sel_hi:[0,0,0]
	v_mfma_scale_f32_16x16x128_f8f6f4 v[58:61], v[160:167], v[184:191], v[58:61], v235, v235 op_sel_hi:[0,0,0]
	v_mfma_scale_f32_16x16x128_f8f6f4 v[54:57], v[152:159], v[192:199], v[54:57], v235, v235 op_sel_hi:[0,0,0]
	v_mfma_scale_f32_16x16x128_f8f6f4 v[46:49], v[160:167], v[192:199], v[46:49], v235, v235 op_sel_hi:[0,0,0]
	v_mfma_scale_f32_16x16x128_f8f6f4 v[38:41], v[152:159], v[200:207], v[38:41], v235, v235 op_sel_hi:[0,0,0]
	v_mfma_scale_f32_16x16x128_f8f6f4 v[30:33], v[160:167], v[200:207], v[30:33], v235, v235 op_sel_hi:[0,0,0]
	v_mfma_scale_f32_16x16x128_f8f6f4 v[22:25], v[152:159], v[208:215], v[22:25], v235, v235 op_sel_hi:[0,0,0]
	v_mfma_scale_f32_16x16x128_f8f6f4 v[14:17], v[160:167], v[208:215], v[14:17], v235, v235 op_sel_hi:[0,0,0]
	s_setprio 0
	s_setprio 1
	v_mfma_scale_f32_16x16x128_f8f6f4 v[50:53], v[168:175], v[184:191], v[50:53], v235, v235 op_sel_hi:[0,0,0]
	v_mfma_scale_f32_16x16x128_f8f6f4 v[42:45], v[176:183], v[184:191], v[42:45], v235, v235 op_sel_hi:[0,0,0]
	v_mfma_scale_f32_16x16x128_f8f6f4 v[34:37], v[168:175], v[192:199], v[34:37], v235, v235 op_sel_hi:[0,0,0]
	v_mfma_scale_f32_16x16x128_f8f6f4 v[26:29], v[176:183], v[192:199], v[26:29], v235, v235 op_sel_hi:[0,0,0]
	v_mfma_scale_f32_16x16x128_f8f6f4 v[18:21], v[168:175], v[200:207], v[18:21], v235, v235 op_sel_hi:[0,0,0]
	v_mfma_scale_f32_16x16x128_f8f6f4 v[10:13], v[176:183], v[200:207], v[10:13], v235, v235 op_sel_hi:[0,0,0]
	v_mfma_scale_f32_16x16x128_f8f6f4 v[6:9], v[168:175], v[208:215], v[6:9], v235, v235 op_sel_hi:[0,0,0]
	v_mfma_scale_f32_16x16x128_f8f6f4 v[2:5], v[176:183], v[208:215], v[2:5], v235, v235 op_sel_hi:[0,0,0]
	s_setprio 0
	s_barrier
; #define PG8_STAGE(bufoff, gbase, voff) do { _Pragma("unroll") for (int _i = 0; _i < 2; ++_i) \
;         __builtin_amdgcn_global_load_lds((const unsigned*)((const char*)(gbase) + (voff)[_i]), (PG8_LAS unsigned*)(lds + (bufoff) + ldsw + _i * 8192), 16, 0, 0); } while (0)
; #define PG8_WAIT_V(n) asm volatile("s_waitcnt vmcnt(" #n ")" ::: "memory")
; #define PG8_WAIT_L(n) asm volatile("s_waitcnt lgkmcnt(" #n ")" ::: "memory")
; #define PG8_BAR __builtin_amdgcn_s_barrier()
; #define PG8_SCHED __builtin_amdgcn_sched_barrier(0)
; #define PG8_STAGEA(bufoff, gbase, h, vsel) do { if constexpr (GATHER) { PG8_STAGE(bufoff, gbase, vsel[h]); } else { PG8_STAGE(bufoff, (gbase) + (h) * hstep, voffA); } } while (0)
; template <class Epi, class Sched, bool ALIGN_EPI = false, bool SP2 = false, bool F8 = false, bool GATHER = false>
; __device__ __forceinline__ void gemm_phase(PG8_LAS unsigned char* lds, const Gemm g, const Sched& S, const Epi& E, const int tid_in) {
;     ...
;             PG8_WAIT_V(8); PG8_WAIT_L(0); PG8_BAR; PG8_MMA(1, 0, At, B0); PG8_MMA(1, 1, At, B1); PG8_BAR; PG8_SCHED;
;             PG8_LDB(B0, 1, 0); PG8_LDB(B1, 1, 1); PG8_SCHED; PG8_LDA(At, 1, 0); PG8_STAGEA(PG8_SA(0, 1), a2, 1, vS);
;             PG8_WAIT_V(8); PG8_WAIT_L(0); PG8_BAR; PG8_MMA(0, 0, At, B0); PG8_MMA(0, 1, At, B1); PG8_BAR; PG8_SCHED;
;             PG8_LDA(At, 1, 1); PG8_STAGE(PG8_SB(1, 0), b3, voffB); PG8_STAGE(PG8_SB(1, 1), b3 + hstep, voffB); PG8_STAGEA(PG8_SA(1, 0), a3, 0, vS);
;             PG8_WAIT_V(8); PG8_WAIT_L(0); PG8_BAR; PG8_MMA(1, 0, At, B0); PG8_MMA(1, 1, At, B1); PG8_BAR; PG8_SCHED;
	s_add_i32 s50, 0, 0x18000
	s_add_i32 s51, 0, 0x1c000
	v_add_u32_e32 v164, s50, v149
	v_add_u32_e32 v180, s51, v149
	ds_read_b128 v[152:155], v164
	ds_read_b128 v[156:159], v164 offset:1024
	ds_read_b128 v[160:163], v164 offset:2048
	ds_read_b128 v[164:167], v164 offset:3072
	ds_read_b128 v[168:171], v180
	ds_read_b128 v[172:175], v180 offset:1024
	ds_read_b128 v[176:179], v180 offset:2048
	ds_read_b128 v[180:183], v180 offset:3072
	s_add_u32 s16, s22, 0x58000
	s_addc_u32 s17, s23, 0
	s_mov_b32 m0, s35
	ds_read_b128 v[184:187], v151 offset:32768
	ds_read_b128 v[188:191], v151 offset:33792
	ds_read_b128 v[192:195], v151 offset:34816
	ds_read_b128 v[196:199], v151 offset:35840
	ds_read_b128 v[200:203], v151 offset:36864
	ds_read_b128 v[204:207], v151 offset:37888
	ds_read_b128 v[208:211], v151 offset:38912
	ds_read_b128 v[212:215], v151 offset:39936
	global_load_lds_dwordx4 v134, s[16:17]
	s_mov_b32 m0, s38
	s_nop 0
	global_load_lds_dwordx4 v132, s[16:17]
	s_waitcnt vmcnt(8)
	s_waitcnt lgkmcnt(0)
	s_barrier
	s_setprio 1
	s_waitcnt lgkmcnt(0)
	v_mfma_scale_f32_16x16x128_f8f6f4 v[126:129], v[152:159], v[184:191], v[126:129], v235, v235 op_sel_hi:[0,0,0]
	v_mfma_scale_f32_16x16x128_f8f6f4 v[122:125], v[160:167], v[184:191], v[122:125], v235, v235 op_sel_hi:[0,0,0]
	v_mfma_scale_f32_16x16x128_f8f6f4 v[118:121], v[152:159], v[192:199], v[118:121], v235, v235 op_sel_hi:[0,0,0]
	v_mfma_scale_f32_16x16x128_f8f6f4 v[110:113], v[160:167], v[192:199], v[110:113], v235, v235 op_sel_hi:[0,0,0]
	v_mfma_scale_f32_16x16x128_f8f6f4 v[102:105], v[152:159], v[200:207], v[102:105], v235, v235 op_sel_hi:[0,0,0]
	v_mfma_scale_f32_16x16x128_f8f6f4 v[94:97], v[160:167], v[200:207], v[94:97], v235, v235 op_sel_hi:[0,0,0]
	v_mfma_scale_f32_16x16x128_f8f6f4 v[86:89], v[152:159], v[208:215], v[86:89], v235, v235 op_sel_hi:[0,0,0]
	v_mfma_scale_f32_16x16x128_f8f6f4 v[78:81], v[160:167], v[208:215], v[78:81], v235, v235 op_sel_hi:[0,0,0]
	s_setprio 0
	s_setprio 1
	v_mfma_scale_f32_16x16x128_f8f6f4 v[114:117], v[168:175], v[184:191], v[114:117], v235, v235 op_sel_hi:[0,0,0]
	v_mfma_scale_f32_16x16x128_f8f6f4 v[106:109], v[176:183], v[184:191], v[106:109], v235, v235 op_sel_hi:[0,0,0]
	v_mfma_scale_f32_16x16x128_f8f6f4 v[98:101], v[168:175], v[192:199], v[98:101], v235, v235 op_sel_hi:[0,0,0]
	v_mfma_scale_f32_16x16x128_f8f6f4 v[90:93], v[176:183], v[192:199], v[90:93], v235, v235 op_sel_hi:[0,0,0]
	v_mfma_scale_f32_16x16x128_f8f6f4 v[82:85], v[168:175], v[200:207], v[82:85], v235, v235 op_sel_hi:[0,0,0]
	v_mfma_scale_f32_16x16x128_f8f6f4 v[74:77], v[176:183], v[200:207], v[74:77], v235, v235 op_sel_hi:[0,0,0]
	v_mfma_scale_f32_16x16x128_f8f6f4 v[70:73], v[168:175], v[208:215], v[70:73], v235, v235 op_sel_hi:[0,0,0]
	v_mfma_scale_f32_16x16x128_f8f6f4 v[66:69], v[176:183], v[208:215], v[66:69], v235, v235 op_sel_hi:[0,0,0]
	s_setprio 0
	s_barrier
	s_add_i32 s16, s50, s28
	v_lshl_add_u64 v[140:141], v[140:141], 0, s[0:1]
	s_mov_b32 m0, s16
	ds_read_b128 v[184:187], v151 offset:49152
	ds_read_b128 v[188:191], v151 offset:50176
	ds_read_b128 v[192:195], v151 offset:51200
	ds_read_b128 v[196:199], v151 offset:52224
	ds_read_b128 v[200:203], v151 offset:53248
	ds_read_b128 v[204:207], v151 offset:54272
	ds_read_b128 v[208:211], v151 offset:55296
	ds_read_b128 v[212:215], v151 offset:56320
	global_load_lds_dwordx4 v[140:141], off
	s_add_i32 m0, s16, 0x2000
	s_add_u32 s16, s20, 0x58080
	v_lshl_add_u64 v[140:141], v[142:143], 0, s[0:1]
	s_addc_u32 s17, s21, 0
	s_add_i32 s20, s51, s28
	global_load_lds_dwordx4 v[140:141], off
	s_mov_b32 m0, s20
	s_nop 0
	global_load_lds_dwordx4 v0, s[16:17]
	s_add_i32 m0, s20, 0x2000
	s_nop 0
	global_load_lds_dwordx4 v130, s[16:17]
	v_lshl_add_u64 v[140:141], v[144:145], 0, s[0:1]
	s_mov_b32 m0, s39
	s_nop 0
	global_load_lds_dwordx4 v[140:141], off
	v_lshl_add_u64 v[140:141], v[146:147], 0, s[0:1]
	s_mov_b32 m0, s40
	s_nop 0
	global_load_lds_dwordx4 v[140:141], off
	s_waitcnt vmcnt(8)
	s_waitcnt lgkmcnt(0)
	s_barrier
	s_setprio 1
	s_waitcnt lgkmcnt(0)
	v_mfma_scale_f32_16x16x128_f8f6f4 v[62:65], v[152:159], v[184:191], v[62:65], v235, v235 op_sel_hi:[0,0,0]
	v_mfma_scale_f32_16x16x128_f8f6f4 v[58:61], v[160:167], v[184:191], v[58:61], v235, v235 op_sel_hi:[0,0,0]
	v_mfma_scale_f32_16x16x128_f8f6f4 v[54:57], v[152:159], v[192:199], v[54:57], v235, v235 op_sel_hi:[0,0,0]
	v_mfma_scale_f32_16x16x128_f8f6f4 v[46:49], v[160:167], v[192:199], v[46:49], v235, v235 op_sel_hi:[0,0,0]
	v_mfma_scale_f32_16x16x128_f8f6f4 v[38:41], v[152:159], v[200:207], v[38:41], v235, v235 op_sel_hi:[0,0,0]
	v_mfma_scale_f32_16x16x128_f8f6f4 v[30:33], v[160:167], v[200:207], v[30:33], v235, v235 op_sel_hi:[0,0,0]
	v_mfma_scale_f32_16x16x128_f8f6f4 v[22:25], v[152:159], v[208:215], v[22:25], v235, v235 op_sel_hi:[0,0,0]
	v_mfma_scale_f32_16x16x128_f8f6f4 v[14:17], v[160:167], v[208:215], v[14:17], v235, v235 op_sel_hi:[0,0,0]
	s_setprio 0
	s_setprio 1
	v_mfma_scale_f32_16x16x128_f8f6f4 v[50:53], v[168:175], v[184:191], v[50:53], v235, v235 op_sel_hi:[0,0,0]
	v_mfma_scale_f32_16x16x128_f8f6f4 v[42:45], v[176:183], v[184:191], v[42:45], v235, v235 op_sel_hi:[0,0,0]
	v_mfma_scale_f32_16x16x128_f8f6f4 v[34:37], v[168:175], v[192:199], v[34:37], v235, v235 op_sel_hi:[0,0,0]
	v_mfma_scale_f32_16x16x128_f8f6f4 v[26:29], v[176:183], v[192:199], v[26:29], v235, v235 op_sel_hi:[0,0,0]
	v_mfma_scale_f32_16x16x128_f8f6f4 v[18:21], v[168:175], v[200:207], v[18:21], v235, v235 op_sel_hi:[0,0,0]
	v_mfma_scale_f32_16x16x128_f8f6f4 v[10:13], v[176:183], v[200:207], v[10:13], v235, v235 op_sel_hi:[0,0,0]
	v_mfma_scale_f32_16x16x128_f8f6f4 v[6:9], v[168:175], v[208:215], v[6:9], v235, v235 op_sel_hi:[0,0,0]
	v_mfma_scale_f32_16x16x128_f8f6f4 v[2:5], v[176:183], v[208:215], v[2:5], v235, v235 op_sel_hi:[0,0,0]
	s_setprio 0
	s_barrier
	s_add_i32 s49, s49, 2
	s_add_u32 s47, s47, 0x100
	s_addc_u32 s48, s48, 0
	s_cmp_gt_u32 s49, 19
	s_mov_b64 s[16:17], s[18:19]
	s_cbranch_scc0 .LBB0_2249
	s_and_b64 vcc, exec, s[12:13]
	s_cbranch_vccz .LBB0_2252
	s_barrier
